# in-projection q/k epilogue: gain vectors loaded once per tile instead of per row group, per-group vmcnt(0) removed so stores are not waited for
# speedup vs baseline: 1.0137x; 1.0137x over previous
; #define LAS __attribute__((address_space(3)))
;     __device__ __forceinline__ void operator()(const Acc& acc, const Unit& u, int wr, int wc, int fr_, int fq_) const {
;     ...
;             for (int m = 0; m < 4; ++m) { const int rt = ai * HALF + wr * 64 + m * 16 + fr;
;                 const int sp = (u.pm & 15) * BM + rt; const float pos = userow ? (float)(sp >> 6) : (float)(sp & 63);
;                 float cs[4], sn[4], ga[4], gb[4];
;                 { const float* gp = g + t0; asm volatile("" : "+v"(gp));
;                   const f32x4 g1 = *(const f32x4*)gp, g2 = *(const f32x4*)(gp + hd2);
; #pragma unroll
;                   for (int p = 0; p < 4; ++p) { ga[p] = g1[p] * osc; gb[p] = g2[p] * osc; } }
; #pragma unroll
;                 for (int p = 0; p < 4; ++p) { const float ang = pos * __builtin_amdgcn_exp2f(-(float)((t0 + p) & (nf - 1)) * (13.287712379549449f / (float)nf));
;                     cs[p] = rope ? __cosf(ang) : 1.f; sn[p] = rope ? __sinf(ang) : 0.f; }
;                 bf16_t* rowp = base + (size_t)(rowbase + rt) * ld + col0;
; #pragma unroll
;                 for (int bj = 0; bj < 2; ++bj) { const f32x4 xs = *(const LAS f32x4*)(X + (rt * 2 + bj) * 4);
;                     const float tot = h128 ? ((xs[0] + xs[1]) + (xs[2] + xs[3])) : ((wc & 2) ? (xs[2] + xs[3]) : (xs[0] + xs[1]));
;                     const float rstd = rsqrtf(tot * inv_w + EPS);
;                     const f32x4 v0 = acc[ai][bj][m][0], v1 = acc[ai][bj][m][1];
;                     float o[8]; const float e[8] = {v0[0], v0[1], v0[2], v0[3], v1[0], v1[1], v1[2], v1[3]};
; #pragma unroll
;                     for (int p = 0; p < 4; ++p) { const float x1 = e[2 * p] * rstd * ga[p], x2 = e[2 * p + 1] * rstd * gb[p];
;                         o[2 * p] = x1 * cs[p] - x2 * sn[p]; o[2 * p + 1] = x2 * cs[p] + x1 * sn[p]; }
;                     *(u32x4*)(rowp + bj * HALF) = pack8(o); }
.LBB0_308:
	s_cmp_lt_i32 s92, 64
	s_cselect_b64 s[6:7], -1, 0
	s_lshl_b32 s0, s92, 8
	s_waitcnt lgkmcnt(0)
	v_cvt_f32_ubyte0_e32 v136, s26
	v_cmp_gt_i32_e64 s[8:9], s26, v160
	s_and_b32 s87, s0, 0xf00
	s_add_i32 s0, s26, -1
	v_div_scale_f32 v137, s[26:27], v136, v136, s84
	v_rcp_f32_e32 v138, v137
	s_waitcnt vmcnt(0)
	v_mov_b32_e32 v194, v128
	v_mov_b32_e32 v195, v129
	v_mov_b32_e32 v196, v130
	v_mov_b32_e32 v197, v131
	v_mov_b32_e32 v198, v132
	v_mov_b32_e32 v199, v133
	v_mov_b32_e32 v200, v134
	v_mov_b32_e32 v201, v135
	v_mul_f32_e32 v178, s43, v128
	v_and_b32_e32 v128, s0, v160
	v_cvt_f32_u32_e32 v128, v128
	v_fma_f32 v139, -v137, v138, 1.0
	v_fmac_f32_e32 v138, v139, v138
	v_div_scale_f32 v139, vcc, s84, v136, s84
	v_mul_f32_e32 v155, v139, v138
	v_fma_f32 v156, -v137, v155, v139
	v_fmac_f32_e32 v155, v156, v138
	v_fma_f32 v137, -v137, v155, v139
	v_div_fmas_f32 v137, v137, v138, v155
	v_div_fixup_f32 v185, v137, v136, s84
	v_add_u32_e32 v136, s87, v171
	v_ashrrev_i32_e32 v136, 6, v136
	v_ashrrev_i32_e32 v155, 31, v154
	v_cvt_f32_i32_e32 v136, v136
	v_mul_f32_e64 v128, v185, -v128
	v_lshl_add_u64 v[156:157], v[154:155], 1, s[88:89]
	v_exp_f32_e32 v155, v128
	v_and_b32_e32 v174, 63, v170
	v_cvt_f32_ubyte0_e32 v173, v174
	v_cndmask_b32_e64 v186, v173, v136, s[8:9]
	v_mul_f32_e32 v128, v186, v155
	v_mul_f32_e32 v128, 0.15915494, v128
	v_mul_f32_e32 v176, s43, v129
	v_cos_f32_e32 v129, v128
	v_sin_f32_e32 v128, v128
	v_mul_f32_e32 v137, s43, v134
	v_mul_f32_e32 v134, s43, v135
	v_cndmask_b32_e64 v135, 1.0, v129, s[6:7]
	v_cndmask_b32_e64 v180, 0, v128, s[6:7]
	v_bitop3_b32 v128, s0, v160, 1 bitop3:0xe0
	v_cvt_f32_u32_e32 v128, v128
	v_mul_f32_e32 v177, s43, v132
	v_mul_f32_e32 v139, s43, v133
	v_mul_f32_e32 v138, s43, v130
	v_mul_f32_e64 v128, v185, -v128
	v_exp_f32_e32 v161, v128
	v_mul_f32_e32 v136, s43, v131
	v_mul_f32_e32 v128, v186, v161
	v_mul_f32_e32 v128, 0.15915494, v128
	v_cos_f32_e32 v129, v128
	v_sin_f32_e32 v128, v128
	v_cndmask_b32_e64 v181, 1.0, v129, s[6:7]
	v_cndmask_b32_e64 v182, 0, v128, s[6:7]
	v_bitop3_b32 v128, s0, v160, 2 bitop3:0xe0
	v_cvt_f32_u32_e32 v128, v128
	v_mul_f32_e64 v128, v185, -v128
	v_exp_f32_e32 v172, v128
	s_nop 0
	v_mul_f32_e32 v128, v186, v172
	v_mul_f32_e32 v128, 0.15915494, v128
	v_cos_f32_e32 v129, v128
	v_sin_f32_e32 v128, v128
	v_cndmask_b32_e64 v183, 1.0, v129, s[6:7]
	v_cndmask_b32_e64 v184, 0, v128, s[6:7]
	v_bitop3_b32 v128, s0, v160, 3 bitop3:0xe0
	v_cvt_f32_u32_e32 v128, v128
	v_mul_f32_e64 v128, v185, -v128
	v_exp_f32_e32 v160, v128
	s_nop 0
	v_mul_f32_e32 v128, v186, v160
	v_mul_f32_e32 v128, 0.15915494, v128
	v_cos_f32_e32 v129, v128
	v_sin_f32_e32 v128, v128
	v_cndmask_b32_e64 v185, 1.0, v129, s[6:7]
	v_cndmask_b32_e64 v186, 0, v128, s[6:7]
	v_add_u32_e32 v128, s35, v171
	v_mad_i64_i32 v[128:129], s[0:1], s86, v128, 0
	v_lshl_add_u64 v[132:133], v[128:129], 1, v[156:157]
	v_fma_f32 v128, s45, v179, v168
	v_cmp_gt_f32_e32 vcc, s85, v128
	v_mul_f32_e32 v129, 0x4b800000, v128
	s_mov_b64 s[0:1], -1
	v_cndmask_b32_e32 v128, v128, v129, vcc
	v_rsq_f32_e32 v128, v128
	s_nop 0
	v_mul_f32_e32 v129, 0x45800000, v128
	v_cndmask_b32_e32 v128, v128, v129, vcc
	v_mul_f32_e32 v130, v125, v128
	v_mul_f32_e32 v129, v124, v128
	v_mul_f32_e32 v130, v177, v130
	v_mul_f32_e32 v129, v178, v129
	v_mul_f32_e32 v131, v180, v130
	v_mul_f32_e32 v130, v135, v130
	v_mul_f32_e32 v179, v127, v128
	v_fma_f32 v131, v135, v129, -v131
	v_fmac_f32_e32 v130, v180, v129
	v_mul_f32_e32 v129, v126, v128
	v_mul_f32_e32 v179, v139, v179
	v_mul_f32_e32 v129, v176, v129
	v_mul_f32_e32 v187, v182, v179
	v_mul_f32_e32 v179, v181, v179
	v_mul_f32_e32 v188, v121, v128
	v_fma_f32 v187, v181, v129, -v187
	v_fmac_f32_e32 v179, v182, v129
	v_mul_f32_e32 v129, v120, v128
	v_mul_f32_e32 v188, v137, v188
	v_mul_f32_e32 v129, v138, v129
	v_mul_f32_e32 v189, v184, v188
	v_mul_f32_e32 v188, v183, v188
	v_fma_f32 v189, v183, v129, -v189
	v_fmac_f32_e32 v188, v184, v129
	v_mul_f32_e32 v129, v122, v128
	v_mul_f32_e32 v128, v123, v128
	v_mul_f32_e32 v128, v134, v128
	v_mul_f32_e32 v129, v136, v129
	v_mul_f32_e32 v190, v186, v128
	v_mul_f32_e32 v191, v185, v128
	v_fma_f32 v190, v185, v129, -v190
	v_fmac_f32_e32 v191, v186, v129
	v_cvt_pk_bf16_f32 v128, v131, v130
	v_cvt_pk_bf16_f32 v129, v187, v179
	v_cvt_pk_bf16_f32 v130, v189, v188
	v_cvt_pk_bf16_f32 v131, v190, v191
	global_store_dwordx4 v[132:133], v[128:131], off
	ds_read_b128 v[128:131], v175 offset:16
	s_and_b64 vcc, exec, s[2:3]
	s_cbranch_vccnz .LBB0_314
	s_and_b64 vcc, exec, s[4:5]
	s_cbranch_vccnz .LBB0_311
	s_waitcnt lgkmcnt(0)
	v_add_f32_e32 v175, v130, v131
	s_mov_b64 s[0:1], 0

; #define LAS __attribute__((address_space(3)))
;     __device__ __forceinline__ void operator()(const Acc& acc, const Unit& u, int wr, int wc, int fr_, int fq_) const {
;     ...
;             for (int m = 0; m < 4; ++m) { const int rt = ai * HALF + wr * 64 + m * 16 + fr;
;                 const int sp = (u.pm & 15) * BM + rt; const float pos = userow ? (float)(sp >> 6) : (float)(sp & 63);
;                 float cs[4], sn[4], ga[4], gb[4];
;                 { const float* gp = g + t0; asm volatile("" : "+v"(gp));
;                   const f32x4 g1 = *(const f32x4*)gp, g2 = *(const f32x4*)(gp + hd2);
; #pragma unroll
;                   for (int p = 0; p < 4; ++p) { ga[p] = g1[p] * osc; gb[p] = g2[p] * osc; } }
;     ...
;                 for (int bj = 0; bj < 2; ++bj) { const f32x4 xs = *(const LAS f32x4*)(X + (rt * 2 + bj) * 4);
;                     const float tot = h128 ? ((xs[0] + xs[1]) + (xs[2] + xs[3])) : ((wc & 2) ? (xs[2] + xs[3]) : (xs[0] + xs[1]));
;                     const float rstd = rsqrtf(tot * inv_w + EPS);
;                     const f32x4 v0 = acc[ai][bj][m][0], v1 = acc[ai][bj][m][1];
;                     float o[8]; const float e[8] = {v0[0], v0[1], v0[2], v0[3], v1[0], v1[1], v1[2], v1[3]};
; #pragma unroll
;                     for (int p = 0; p < 4; ++p) { const float x1 = e[2 * p] * rstd * ga[p], x2 = e[2 * p + 1] * rstd * gb[p];
;                         o[2 * p] = x1 * cs[p] - x2 * sn[p]; o[2 * p + 1] = x2 * cs[p] + x1 * sn[p]; }
;                     *(u32x4*)(rowp + bj * HALF) = pack8(o); }
.LBB0_316:
	s_waitcnt lgkmcnt(0)
	v_fma_f32 v128, s45, v175, v168
	v_cmp_gt_f32_e32 vcc, s85, v128
	v_mul_f32_e32 v129, 0x4b800000, v128
	s_nop 0
	v_cndmask_b32_e32 v128, v128, v129, vcc
	v_rsq_f32_e32 v128, v128
	s_nop 0
	v_mul_f32_e32 v129, 0x45800000, v128
	v_cndmask_b32_e32 v128, v128, v129, vcc
	v_mul_f32_e32 v130, v117, v128
	v_mul_f32_e32 v129, v116, v128
	v_mul_f32_e32 v130, v177, v130
	v_mul_f32_e32 v129, v178, v129
	v_mul_f32_e32 v131, v180, v130
	v_fma_f32 v131, v135, v129, -v131
	v_mul_f32_e32 v130, v135, v130
	v_mul_f32_e32 v135, v119, v128
	v_fmac_f32_e32 v130, v180, v129
	v_mul_f32_e32 v129, v118, v128
	v_mul_f32_e32 v135, v139, v135
	v_mul_f32_e32 v129, v176, v129
	v_mul_f32_e32 v139, v182, v135
	v_mul_f32_e32 v135, v181, v135
	v_fma_f32 v139, v181, v129, -v139
	v_fmac_f32_e32 v135, v182, v129
	v_mul_f32_e32 v129, v112, v128
	v_mul_f32_e32 v129, v138, v129
	v_mul_f32_e32 v138, v113, v128
	v_mul_f32_e32 v137, v137, v138
	v_mul_f32_e32 v138, v184, v137
	v_mul_f32_e32 v137, v183, v137
	v_fma_f32 v138, v183, v129, -v138
	v_fmac_f32_e32 v137, v184, v129
	v_mul_f32_e32 v129, v114, v128
	v_mul_f32_e32 v128, v115, v128
	v_mul_f32_e32 v128, v134, v128
	v_mul_f32_e32 v129, v136, v129
	v_mul_f32_e32 v134, v186, v128
	v_mul_f32_e32 v136, v185, v128
	v_fma_f32 v134, v185, v129, -v134
	v_fmac_f32_e32 v136, v186, v129
	v_cvt_pk_bf16_f32 v128, v131, v130
	v_cvt_pk_bf16_f32 v129, v139, v135
	v_cvt_pk_bf16_f32 v130, v138, v137
	v_cvt_pk_bf16_f32 v131, v134, v136
	global_store_dwordx4 v[132:133], v[128:131], off offset:256
	s_nop 1
	v_mov_b64_e32 v[128:129], v[158:159]
	v_add_u32_e32 v187, 16, v171
	v_lshl_add_u64 v[132:133], v[128:129], 0, s[22:23]
	v_mov_b32_e32 v128, v194
	v_mov_b32_e32 v129, v195
	v_mov_b32_e32 v130, v196
	v_mov_b32_e32 v131, v197
	v_mov_b32_e32 v132, v198
	v_mov_b32_e32 v133, v199
	v_mov_b32_e32 v134, v200
	v_mov_b32_e32 v135, v201
	v_lshlrev_b32_e32 v181, 5, v187
	v_add_u32_e32 v136, 0, v181
	v_add_u32_e32 v136, 0x20000, v136
	ds_read_b128 v[136:139], v136
	s_and_b64 vcc, exec, s[2:3]
	s_mov_b64 s[0:1], -1
	s_cbranch_vccnz .LBB0_322
	s_and_b64 vcc, exec, s[4:5]
	s_cbranch_vccnz .LBB0_319
	s_waitcnt lgkmcnt(0)
	v_add_f32_e32 v188, v138, v139
	s_mov_b64 s[0:1], 0

; #define LAS __attribute__((address_space(3)))
;     __device__ __forceinline__ void operator()(const Acc& acc, const Unit& u, int wr, int wc, int fr_, int fq_) const {
;     ...
;             for (int m = 0; m < 4; ++m) { const int rt = ai * HALF + wr * 64 + m * 16 + fr;
;                 const int sp = (u.pm & 15) * BM + rt; const float pos = userow ? (float)(sp >> 6) : (float)(sp & 63);
;                 float cs[4], sn[4], ga[4], gb[4];
;                 { const float* gp = g + t0; asm volatile("" : "+v"(gp));
;                   const f32x4 g1 = *(const f32x4*)gp, g2 = *(const f32x4*)(gp + hd2);
; #pragma unroll
;                   for (int p = 0; p < 4; ++p) { ga[p] = g1[p] * osc; gb[p] = g2[p] * osc; } }
; #pragma unroll
;                 for (int p = 0; p < 4; ++p) { const float ang = pos * __builtin_amdgcn_exp2f(-(float)((t0 + p) & (nf - 1)) * (13.287712379549449f / (float)nf));
;                     cs[p] = rope ? __cosf(ang) : 1.f; sn[p] = rope ? __sinf(ang) : 0.f; }
;                 bf16_t* rowp = base + (size_t)(rowbase + rt) * ld + col0;
; #pragma unroll
;                 for (int bj = 0; bj < 2; ++bj) { const f32x4 xs = *(const LAS f32x4*)(X + (rt * 2 + bj) * 4);
;                     const float tot = h128 ? ((xs[0] + xs[1]) + (xs[2] + xs[3])) : ((wc & 2) ? (xs[2] + xs[3]) : (xs[0] + xs[1]));
;                     const float rstd = rsqrtf(tot * inv_w + EPS);
;                     const f32x4 v0 = acc[ai][bj][m][0], v1 = acc[ai][bj][m][1];
;                     float o[8]; const float e[8] = {v0[0], v0[1], v0[2], v0[3], v1[0], v1[1], v1[2], v1[3]};
; #pragma unroll
;                     for (int p = 0; p < 4; ++p) { const float x1 = e[2 * p] * rstd * ga[p], x2 = e[2 * p + 1] * rstd * gb[p];
;                         o[2 * p] = x1 * cs[p] - x2 * sn[p]; o[2 * p + 1] = x2 * cs[p] + x1 * sn[p]; }
;                     *(u32x4*)(rowp + bj * HALF) = pack8(o); }
.LBB0_324:
	s_waitcnt lgkmcnt(0)
	v_add_u32_e32 v137, s87, v187
	v_ashrrev_i32_e32 v137, 6, v137
	v_cvt_f32_i32_e32 v137, v137
	v_add_u32_e32 v136, 16, v170
	v_and_b32_e32 v136, 63, v136
	v_cvt_f32_ubyte0_e32 v175, v136
	v_cndmask_b32_e64 v185, v175, v137, s[8:9]
	s_nop 0
	v_mul_f32_e32 v178, s43, v128
	v_mul_f32_e32 v128, v185, v155
	v_mul_f32_e32 v128, 0.15915494, v128
	v_mul_f32_e32 v176, s43, v129
	v_cos_f32_e32 v129, v128
	v_sin_f32_e32 v128, v128
	v_mul_f32_e32 v137, s43, v134
	v_mul_f32_e32 v134, s43, v135
	v_cndmask_b32_e64 v135, 1.0, v129, s[6:7]
	v_cndmask_b32_e64 v179, 0, v128, s[6:7]
	v_mul_f32_e32 v128, v185, v161
	v_mul_f32_e32 v128, 0.15915494, v128
	v_cos_f32_e32 v129, v128
	v_sin_f32_e32 v128, v128
	v_mul_f32_e32 v177, s43, v132
	v_mul_f32_e32 v139, s43, v133
	v_cndmask_b32_e64 v180, 1.0, v129, s[6:7]
	v_cndmask_b32_e64 v183, 0, v128, s[6:7]
	v_mul_f32_e32 v128, v185, v172
	v_mul_f32_e32 v128, 0.15915494, v128
	v_cos_f32_e32 v129, v128
	v_sin_f32_e32 v128, v128
	v_mul_f32_e32 v138, s43, v130
	v_mul_f32_e32 v136, s43, v131
	v_cndmask_b32_e64 v182, 1.0, v129, s[6:7]
	v_cndmask_b32_e64 v184, 0, v128, s[6:7]
	v_mul_f32_e32 v128, v185, v160
	v_mul_f32_e32 v128, 0.15915494, v128
	v_cos_f32_e32 v129, v128
	v_sin_f32_e32 v128, v128
	v_cndmask_b32_e64 v185, 1.0, v129, s[6:7]
	v_cndmask_b32_e64 v186, 0, v128, s[6:7]
	v_add_u32_e32 v128, s35, v187
	v_mad_i64_i32 v[128:129], s[0:1], s86, v128, 0
	v_lshl_add_u64 v[132:133], v[128:129], 1, v[156:157]
	v_fma_f32 v128, s45, v188, v168
	v_cmp_gt_f32_e32 vcc, s85, v128
	v_mul_f32_e32 v129, 0x4b800000, v128
	s_mov_b64 s[0:1], -1
	v_cndmask_b32_e32 v128, v128, v129, vcc
	v_rsq_f32_e32 v128, v128
	s_nop 0
	v_mul_f32_e32 v129, 0x45800000, v128
	v_cndmask_b32_e32 v128, v128, v129, vcc
	v_mul_f32_e32 v130, v109, v128
	v_mul_f32_e32 v129, v108, v128
	v_mul_f32_e32 v130, v177, v130
	v_mul_f32_e32 v129, v178, v129
	v_mul_f32_e32 v131, v179, v130
	v_mul_f32_e32 v130, v135, v130
	v_mul_f32_e32 v187, v111, v128
	v_fma_f32 v131, v135, v129, -v131
	v_fmac_f32_e32 v130, v179, v129
	v_mul_f32_e32 v129, v110, v128
	v_mul_f32_e32 v187, v139, v187
	v_mul_f32_e32 v129, v176, v129
	v_mul_f32_e32 v188, v183, v187
	v_mul_f32_e32 v187, v180, v187
	v_mul_f32_e32 v189, v105, v128
	v_fma_f32 v188, v180, v129, -v188
	v_fmac_f32_e32 v187, v183, v129
	v_mul_f32_e32 v129, v104, v128
	v_mul_f32_e32 v189, v137, v189
	v_mul_f32_e32 v129, v138, v129
	v_mul_f32_e32 v190, v184, v189
	v_mul_f32_e32 v189, v182, v189
	v_fma_f32 v190, v182, v129, -v190
	v_fmac_f32_e32 v189, v184, v129
	v_mul_f32_e32 v129, v106, v128
	v_mul_f32_e32 v128, v107, v128
	v_mul_f32_e32 v128, v134, v128
	v_mul_f32_e32 v129, v136, v129
	v_mul_f32_e32 v191, v186, v128
	v_mul_f32_e32 v192, v185, v128
	v_cvt_pk_bf16_f32 v128, v131, v130
	v_fma_f32 v191, v185, v129, -v191
	v_fmac_f32_e32 v192, v186, v129
	v_cvt_pk_bf16_f32 v129, v188, v187
	v_cvt_pk_bf16_f32 v130, v190, v189
	v_cvt_pk_bf16_f32 v131, v191, v192
	global_store_dwordx4 v[132:133], v[128:131], off
	s_and_b64 vcc, exec, s[2:3]
	s_nop 0
	v_add_u32_e32 v128, s95, v181
	ds_read_b128 v[128:131], v128 offset:16
	s_cbranch_vccnz .LBB0_330
	s_and_b64 vcc, exec, s[4:5]
	s_cbranch_vccnz .LBB0_327
	s_waitcnt lgkmcnt(0)
	v_add_f32_e32 v181, v130, v131
	s_mov_b64 s[0:1], 0

; #define LAS __attribute__((address_space(3)))
;     __device__ __forceinline__ void operator()(const Acc& acc, const Unit& u, int wr, int wc, int fr_, int fq_) const {
;     ...
;             for (int m = 0; m < 4; ++m) { const int rt = ai * HALF + wr * 64 + m * 16 + fr;
;                 const int sp = (u.pm & 15) * BM + rt; const float pos = userow ? (float)(sp >> 6) : (float)(sp & 63);
;                 float cs[4], sn[4], ga[4], gb[4];
;                 { const float* gp = g + t0; asm volatile("" : "+v"(gp));
;                   const f32x4 g1 = *(const f32x4*)gp, g2 = *(const f32x4*)(gp + hd2);
; #pragma unroll
;                   for (int p = 0; p < 4; ++p) { ga[p] = g1[p] * osc; gb[p] = g2[p] * osc; } }
;     ...
;                 for (int bj = 0; bj < 2; ++bj) { const f32x4 xs = *(const LAS f32x4*)(X + (rt * 2 + bj) * 4);
;                     const float tot = h128 ? ((xs[0] + xs[1]) + (xs[2] + xs[3])) : ((wc & 2) ? (xs[2] + xs[3]) : (xs[0] + xs[1]));
;                     const float rstd = rsqrtf(tot * inv_w + EPS);
;                     const f32x4 v0 = acc[ai][bj][m][0], v1 = acc[ai][bj][m][1];
;                     float o[8]; const float e[8] = {v0[0], v0[1], v0[2], v0[3], v1[0], v1[1], v1[2], v1[3]};
; #pragma unroll
;                     for (int p = 0; p < 4; ++p) { const float x1 = e[2 * p] * rstd * ga[p], x2 = e[2 * p + 1] * rstd * gb[p];
;                         o[2 * p] = x1 * cs[p] - x2 * sn[p]; o[2 * p + 1] = x2 * cs[p] + x1 * sn[p]; }
;                     *(u32x4*)(rowp + bj * HALF) = pack8(o); }
.LBB0_332:
	s_waitcnt lgkmcnt(0)
	v_fma_f32 v128, s45, v181, v168
	v_cmp_gt_f32_e32 vcc, s85, v128
	v_mul_f32_e32 v129, 0x4b800000, v128
	s_nop 0
	v_cndmask_b32_e32 v128, v128, v129, vcc
	v_rsq_f32_e32 v128, v128
	s_nop 0
	v_mul_f32_e32 v129, 0x45800000, v128
	v_cndmask_b32_e32 v128, v128, v129, vcc
	v_mul_f32_e32 v130, v101, v128
	v_mul_f32_e32 v129, v100, v128
	v_mul_f32_e32 v130, v177, v130
	v_mul_f32_e32 v129, v178, v129
	v_mul_f32_e32 v131, v179, v130
	v_fma_f32 v131, v135, v129, -v131
	v_mul_f32_e32 v130, v135, v130
	v_mul_f32_e32 v135, v103, v128
	v_fmac_f32_e32 v130, v179, v129
	v_mul_f32_e32 v129, v102, v128
	v_mul_f32_e32 v135, v139, v135
	v_mul_f32_e32 v129, v176, v129
	v_mul_f32_e32 v139, v183, v135
	v_mul_f32_e32 v135, v180, v135
	v_fma_f32 v139, v180, v129, -v139
	v_fmac_f32_e32 v135, v183, v129
	v_mul_f32_e32 v129, v96, v128
	v_mul_f32_e32 v129, v138, v129
	v_mul_f32_e32 v138, v97, v128
	v_mul_f32_e32 v137, v137, v138
	v_mul_f32_e32 v138, v184, v137
	v_mul_f32_e32 v137, v182, v137
	v_fma_f32 v138, v182, v129, -v138
	v_fmac_f32_e32 v137, v184, v129
	v_mul_f32_e32 v129, v98, v128
	v_mul_f32_e32 v128, v99, v128
	v_mul_f32_e32 v128, v134, v128
	v_mul_f32_e32 v129, v136, v129
	v_mul_f32_e32 v134, v186, v128
	v_mul_f32_e32 v136, v185, v128
	v_fma_f32 v134, v185, v129, -v134
	v_fmac_f32_e32 v136, v186, v129
	v_cvt_pk_bf16_f32 v128, v131, v130
	v_cvt_pk_bf16_f32 v129, v139, v135
	v_cvt_pk_bf16_f32 v130, v138, v137
	v_cvt_pk_bf16_f32 v131, v134, v136
	global_store_dwordx4 v[132:133], v[128:131], off offset:256
	s_nop 1
	v_mov_b64_e32 v[128:129], v[158:159]
	v_add_u32_e32 v187, 32, v171
	v_lshl_add_u64 v[132:133], v[128:129], 0, s[22:23]
	v_mov_b32_e32 v128, v194
	v_mov_b32_e32 v129, v195
	v_mov_b32_e32 v130, v196
	v_mov_b32_e32 v131, v197
	v_mov_b32_e32 v132, v198
	v_mov_b32_e32 v133, v199
	v_mov_b32_e32 v134, v200
	v_mov_b32_e32 v135, v201
	v_lshlrev_b32_e32 v179, 5, v187
	v_add_u32_e32 v136, 0, v179
	v_add_u32_e32 v136, 0x20000, v136
	ds_read_b128 v[136:139], v136
	s_and_b64 vcc, exec, s[2:3]
	s_mov_b64 s[0:1], -1
	s_cbranch_vccnz .LBB0_338
	s_and_b64 vcc, exec, s[4:5]
	s_cbranch_vccnz .LBB0_335
	s_waitcnt lgkmcnt(0)
	v_add_f32_e32 v188, v138, v139
	s_mov_b64 s[0:1], 0

; #define LAS __attribute__((address_space(3)))
;     __device__ __forceinline__ void operator()(const Acc& acc, const Unit& u, int wr, int wc, int fr_, int fq_) const {
;     ...
;             for (int m = 0; m < 4; ++m) { const int rt = ai * HALF + wr * 64 + m * 16 + fr;
;                 const int sp = (u.pm & 15) * BM + rt; const float pos = userow ? (float)(sp >> 6) : (float)(sp & 63);
;                 float cs[4], sn[4], ga[4], gb[4];
;                 { const float* gp = g + t0; asm volatile("" : "+v"(gp));
;                   const f32x4 g1 = *(const f32x4*)gp, g2 = *(const f32x4*)(gp + hd2);
; #pragma unroll
;                   for (int p = 0; p < 4; ++p) { ga[p] = g1[p] * osc; gb[p] = g2[p] * osc; } }
; #pragma unroll
;                 for (int p = 0; p < 4; ++p) { const float ang = pos * __builtin_amdgcn_exp2f(-(float)((t0 + p) & (nf - 1)) * (13.287712379549449f / (float)nf));
;                     cs[p] = rope ? __cosf(ang) : 1.f; sn[p] = rope ? __sinf(ang) : 0.f; }
;                 bf16_t* rowp = base + (size_t)(rowbase + rt) * ld + col0;
; #pragma unroll
;                 for (int bj = 0; bj < 2; ++bj) { const f32x4 xs = *(const LAS f32x4*)(X + (rt * 2 + bj) * 4);
;                     const float tot = h128 ? ((xs[0] + xs[1]) + (xs[2] + xs[3])) : ((wc & 2) ? (xs[2] + xs[3]) : (xs[0] + xs[1]));
;                     const float rstd = rsqrtf(tot * inv_w + EPS);
;                     const f32x4 v0 = acc[ai][bj][m][0], v1 = acc[ai][bj][m][1];
;                     float o[8]; const float e[8] = {v0[0], v0[1], v0[2], v0[3], v1[0], v1[1], v1[2], v1[3]};
; #pragma unroll
;                     for (int p = 0; p < 4; ++p) { const float x1 = e[2 * p] * rstd * ga[p], x2 = e[2 * p + 1] * rstd * gb[p];
;                         o[2 * p] = x1 * cs[p] - x2 * sn[p]; o[2 * p + 1] = x2 * cs[p] + x1 * sn[p]; }
;                     *(u32x4*)(rowp + bj * HALF) = pack8(o); }
.LBB0_340:
	s_waitcnt lgkmcnt(0)
	v_add_u32_e32 v137, s87, v187
	v_ashrrev_i32_e32 v137, 6, v137
	v_cvt_f32_i32_e32 v137, v137
	v_xor_b32_e32 v136, 32, v174
	v_cvt_f32_ubyte0_e32 v174, v136
	s_nop 0
	v_mul_f32_e32 v178, s43, v128
	v_cndmask_b32_e64 v185, v174, v137, s[8:9]
	v_mul_f32_e32 v128, v185, v155
	v_mul_f32_e32 v128, 0.15915494, v128
	v_mul_f32_e32 v176, s43, v129
	v_cos_f32_e32 v129, v128
	v_sin_f32_e32 v128, v128
	v_mul_f32_e32 v137, s43, v134
	v_mul_f32_e32 v134, s43, v135
	v_cndmask_b32_e64 v135, 1.0, v129, s[6:7]
	v_cndmask_b32_e64 v180, 0, v128, s[6:7]
	v_mul_f32_e32 v128, v185, v161
	v_mul_f32_e32 v128, 0.15915494, v128
	v_cos_f32_e32 v129, v128
	v_sin_f32_e32 v128, v128
	v_mul_f32_e32 v177, s43, v132
	v_mul_f32_e32 v139, s43, v133
	v_cndmask_b32_e64 v181, 1.0, v129, s[6:7]
	v_cndmask_b32_e64 v183, 0, v128, s[6:7]
	v_mul_f32_e32 v128, v185, v172
	v_mul_f32_e32 v128, 0.15915494, v128
	v_cos_f32_e32 v129, v128
	v_sin_f32_e32 v128, v128
	v_mul_f32_e32 v138, s43, v130
	v_mul_f32_e32 v136, s43, v131
	v_cndmask_b32_e64 v182, 1.0, v129, s[6:7]
	v_cndmask_b32_e64 v184, 0, v128, s[6:7]
	v_mul_f32_e32 v128, v185, v160
	v_mul_f32_e32 v128, 0.15915494, v128
	v_cos_f32_e32 v129, v128
	v_sin_f32_e32 v128, v128
	v_cndmask_b32_e64 v185, 1.0, v129, s[6:7]
	v_cndmask_b32_e64 v186, 0, v128, s[6:7]
	v_add_u32_e32 v128, s35, v187
	v_mad_i64_i32 v[128:129], s[0:1], s86, v128, 0
	v_lshl_add_u64 v[132:133], v[128:129], 1, v[156:157]
	v_fma_f32 v128, s45, v188, v168
	v_cmp_gt_f32_e32 vcc, s85, v128
	v_mul_f32_e32 v129, 0x4b800000, v128
	s_mov_b64 s[0:1], -1
	v_cndmask_b32_e32 v128, v128, v129, vcc
	v_rsq_f32_e32 v128, v128
	s_nop 0
	v_mul_f32_e32 v129, 0x45800000, v128
	v_cndmask_b32_e32 v128, v128, v129, vcc
	v_mul_f32_e32 v130, v93, v128
	v_mul_f32_e32 v129, v92, v128
	v_mul_f32_e32 v130, v177, v130
	v_mul_f32_e32 v129, v178, v129
	v_mul_f32_e32 v131, v180, v130
	v_mul_f32_e32 v130, v135, v130
	v_mul_f32_e32 v187, v95, v128
	v_fma_f32 v131, v135, v129, -v131
	v_fmac_f32_e32 v130, v180, v129
	v_mul_f32_e32 v129, v94, v128
	v_mul_f32_e32 v187, v139, v187
	v_mul_f32_e32 v129, v176, v129
	v_mul_f32_e32 v188, v183, v187
	v_mul_f32_e32 v187, v181, v187
	v_mul_f32_e32 v189, v89, v128
	v_fma_f32 v188, v181, v129, -v188
	v_fmac_f32_e32 v187, v183, v129
	v_mul_f32_e32 v129, v88, v128
	v_mul_f32_e32 v189, v137, v189
	v_mul_f32_e32 v129, v138, v129
	v_mul_f32_e32 v190, v184, v189
	v_mul_f32_e32 v189, v182, v189
	v_fma_f32 v190, v182, v129, -v190
	v_fmac_f32_e32 v189, v184, v129
	v_mul_f32_e32 v129, v90, v128
	v_mul_f32_e32 v128, v91, v128
	v_mul_f32_e32 v128, v134, v128
	v_mul_f32_e32 v129, v136, v129
	v_mul_f32_e32 v191, v186, v128
	v_mul_f32_e32 v192, v185, v128
	v_cvt_pk_bf16_f32 v128, v131, v130
	v_fma_f32 v191, v185, v129, -v191
	v_fmac_f32_e32 v192, v186, v129
	v_cvt_pk_bf16_f32 v129, v188, v187
	v_cvt_pk_bf16_f32 v130, v190, v189
	v_cvt_pk_bf16_f32 v131, v191, v192
	global_store_dwordx4 v[132:133], v[128:131], off
	s_and_b64 vcc, exec, s[2:3]
	s_nop 0
	v_add_u32_e32 v128, s95, v179
	ds_read_b128 v[128:131], v128 offset:16
	s_cbranch_vccnz .LBB0_346
	s_and_b64 vcc, exec, s[4:5]
	s_cbranch_vccnz .LBB0_343
	s_waitcnt lgkmcnt(0)
	v_add_f32_e32 v179, v130, v131
	s_mov_b64 s[0:1], 0

; #define LAS __attribute__((address_space(3)))
;     __device__ __forceinline__ void operator()(const Acc& acc, const Unit& u, int wr, int wc, int fr_, int fq_) const {
;     ...
;             for (int m = 0; m < 4; ++m) { const int rt = ai * HALF + wr * 64 + m * 16 + fr;
;                 const int sp = (u.pm & 15) * BM + rt; const float pos = userow ? (float)(sp >> 6) : (float)(sp & 63);
;                 float cs[4], sn[4], ga[4], gb[4];
;                 { const float* gp = g + t0; asm volatile("" : "+v"(gp));
;                   const f32x4 g1 = *(const f32x4*)gp, g2 = *(const f32x4*)(gp + hd2);
; #pragma unroll
;                   for (int p = 0; p < 4; ++p) { ga[p] = g1[p] * osc; gb[p] = g2[p] * osc; } }
;     ...
;                 for (int bj = 0; bj < 2; ++bj) { const f32x4 xs = *(const LAS f32x4*)(X + (rt * 2 + bj) * 4);
;                     const float tot = h128 ? ((xs[0] + xs[1]) + (xs[2] + xs[3])) : ((wc & 2) ? (xs[2] + xs[3]) : (xs[0] + xs[1]));
;                     const float rstd = rsqrtf(tot * inv_w + EPS);
;                     const f32x4 v0 = acc[ai][bj][m][0], v1 = acc[ai][bj][m][1];
;                     float o[8]; const float e[8] = {v0[0], v0[1], v0[2], v0[3], v1[0], v1[1], v1[2], v1[3]};
; #pragma unroll
;                     for (int p = 0; p < 4; ++p) { const float x1 = e[2 * p] * rstd * ga[p], x2 = e[2 * p + 1] * rstd * gb[p];
;                         o[2 * p] = x1 * cs[p] - x2 * sn[p]; o[2 * p + 1] = x2 * cs[p] + x1 * sn[p]; }
;                     *(u32x4*)(rowp + bj * HALF) = pack8(o); }
.LBB0_348:
	s_waitcnt lgkmcnt(0)
	v_fma_f32 v128, s45, v179, v168
	v_cmp_gt_f32_e32 vcc, s85, v128
	v_mul_f32_e32 v129, 0x4b800000, v128
	s_nop 0
	v_cndmask_b32_e32 v128, v128, v129, vcc
	v_rsq_f32_e32 v128, v128
	s_nop 0
	v_mul_f32_e32 v129, 0x45800000, v128
	v_cndmask_b32_e32 v128, v128, v129, vcc
	v_mul_f32_e32 v130, v85, v128
	v_mul_f32_e32 v129, v84, v128
	v_mul_f32_e32 v130, v177, v130
	v_mul_f32_e32 v129, v178, v129
	v_mul_f32_e32 v131, v180, v130
	v_fma_f32 v131, v135, v129, -v131
	v_mul_f32_e32 v130, v135, v130
	v_mul_f32_e32 v135, v87, v128
	v_fmac_f32_e32 v130, v180, v129
	v_mul_f32_e32 v129, v86, v128
	v_mul_f32_e32 v135, v139, v135
	v_mul_f32_e32 v129, v176, v129
	v_mul_f32_e32 v139, v183, v135
	v_mul_f32_e32 v135, v181, v135
	v_fma_f32 v139, v181, v129, -v139
	v_fmac_f32_e32 v135, v183, v129
	v_mul_f32_e32 v129, v80, v128
	v_mul_f32_e32 v129, v138, v129
	v_mul_f32_e32 v138, v81, v128
	v_mul_f32_e32 v137, v137, v138
	v_mul_f32_e32 v138, v184, v137
	v_mul_f32_e32 v137, v182, v137
	v_fma_f32 v138, v182, v129, -v138
	v_fmac_f32_e32 v137, v184, v129
	v_mul_f32_e32 v129, v82, v128
	v_mul_f32_e32 v128, v83, v128
	v_mul_f32_e32 v128, v134, v128
	v_mul_f32_e32 v129, v136, v129
	v_mul_f32_e32 v134, v186, v128
	v_mul_f32_e32 v136, v185, v128
	v_fma_f32 v134, v185, v129, -v134
	v_fmac_f32_e32 v136, v186, v129
	v_cvt_pk_bf16_f32 v128, v131, v130
	v_cvt_pk_bf16_f32 v129, v139, v135
	v_cvt_pk_bf16_f32 v130, v138, v137
	v_cvt_pk_bf16_f32 v131, v134, v136
	global_store_dwordx4 v[132:133], v[128:131], off offset:256
	s_nop 1
	v_mov_b64_e32 v[128:129], v[158:159]
	v_add_u32_e32 v188, 48, v171
	v_lshl_add_u64 v[132:133], v[128:129], 0, s[22:23]
	v_mov_b32_e32 v128, v194
	v_mov_b32_e32 v129, v195
	v_mov_b32_e32 v130, v196
	v_mov_b32_e32 v131, v197
	v_mov_b32_e32 v132, v198
	v_mov_b32_e32 v133, v199
	v_mov_b32_e32 v134, v200
	v_mov_b32_e32 v135, v201
	v_lshlrev_b32_e32 v182, 5, v188
	v_add_u32_e32 v136, 0, v182
	v_add_u32_e32 v136, 0x20000, v136
	ds_read_b128 v[136:139], v136
	s_and_b64 vcc, exec, s[2:3]
	s_mov_b64 s[0:1], -1
	s_cbranch_vccnz .LBB0_354
	s_and_b64 vcc, exec, s[4:5]
	s_cbranch_vccnz .LBB0_351
	s_waitcnt lgkmcnt(0)
	v_add_f32_e32 v189, v138, v139
	s_mov_b64 s[0:1], 0

; #define LAS __attribute__((address_space(3)))
;     __device__ __forceinline__ void operator()(const Acc& acc, const Unit& u, int wr, int wc, int fr_, int fq_) const {
;     ...
;             for (int m = 0; m < 4; ++m) { const int rt = ai * HALF + wr * 64 + m * 16 + fr;
;                 const int sp = (u.pm & 15) * BM + rt; const float pos = userow ? (float)(sp >> 6) : (float)(sp & 63);
;                 float cs[4], sn[4], ga[4], gb[4];
;                 { const float* gp = g + t0; asm volatile("" : "+v"(gp));
;                   const f32x4 g1 = *(const f32x4*)gp, g2 = *(const f32x4*)(gp + hd2);
; #pragma unroll
;                   for (int p = 0; p < 4; ++p) { ga[p] = g1[p] * osc; gb[p] = g2[p] * osc; } }
; #pragma unroll
;                 for (int p = 0; p < 4; ++p) { const float ang = pos * __builtin_amdgcn_exp2f(-(float)((t0 + p) & (nf - 1)) * (13.287712379549449f / (float)nf));
;                     cs[p] = rope ? __cosf(ang) : 1.f; sn[p] = rope ? __sinf(ang) : 0.f; }
;                 bf16_t* rowp = base + (size_t)(rowbase + rt) * ld + col0;
; #pragma unroll
;                 for (int bj = 0; bj < 2; ++bj) { const f32x4 xs = *(const LAS f32x4*)(X + (rt * 2 + bj) * 4);
;                     const float tot = h128 ? ((xs[0] + xs[1]) + (xs[2] + xs[3])) : ((wc & 2) ? (xs[2] + xs[3]) : (xs[0] + xs[1]));
;                     const float rstd = rsqrtf(tot * inv_w + EPS);
;                     const f32x4 v0 = acc[ai][bj][m][0], v1 = acc[ai][bj][m][1];
;                     float o[8]; const float e[8] = {v0[0], v0[1], v0[2], v0[3], v1[0], v1[1], v1[2], v1[3]};
; #pragma unroll
;                     for (int p = 0; p < 4; ++p) { const float x1 = e[2 * p] * rstd * ga[p], x2 = e[2 * p + 1] * rstd * gb[p];
;                         o[2 * p] = x1 * cs[p] - x2 * sn[p]; o[2 * p + 1] = x2 * cs[p] + x1 * sn[p]; }
;                     *(u32x4*)(rowp + bj * HALF) = pack8(o); }
.LBB0_356:
	s_waitcnt lgkmcnt(0)
	v_add_u32_e32 v137, s87, v188
	v_ashrrev_i32_e32 v137, 6, v137
	v_cvt_f32_i32_e32 v137, v137
	v_add_u32_e32 v136, 48, v170
	v_and_b32_e32 v136, 63, v136
	v_cvt_f32_ubyte0_e32 v176, v136
	v_cndmask_b32_e64 v186, v176, v137, s[8:9]
	s_nop 0
	v_mul_f32_e32 v179, s43, v128
	v_mul_f32_e32 v128, v186, v155
	v_mul_f32_e32 v128, 0.15915494, v128
	v_mul_f32_e32 v177, s43, v129
	v_cos_f32_e32 v129, v128
	v_sin_f32_e32 v128, v128
	v_mul_f32_e32 v137, s43, v134
	v_mul_f32_e32 v134, s43, v135
	v_cndmask_b32_e64 v135, 1.0, v129, s[6:7]
	v_cndmask_b32_e64 v180, 0, v128, s[6:7]
	v_mul_f32_e32 v128, v186, v161
	v_mul_f32_e32 v128, 0.15915494, v128
	v_cos_f32_e32 v129, v128
	v_sin_f32_e32 v128, v128
	v_mul_f32_e32 v178, s43, v132
	v_mul_f32_e32 v139, s43, v133
	v_cndmask_b32_e64 v181, 1.0, v129, s[6:7]
	v_cndmask_b32_e64 v184, 0, v128, s[6:7]
	v_mul_f32_e32 v128, v186, v172
	v_mul_f32_e32 v128, 0.15915494, v128
	v_cos_f32_e32 v129, v128
	v_sin_f32_e32 v128, v128
	v_mul_f32_e32 v138, s43, v130
	v_mul_f32_e32 v136, s43, v131
	v_cndmask_b32_e64 v183, 1.0, v129, s[6:7]
	v_cndmask_b32_e64 v185, 0, v128, s[6:7]
	v_mul_f32_e32 v128, v186, v160
	v_mul_f32_e32 v128, 0.15915494, v128
	v_cos_f32_e32 v129, v128
	v_sin_f32_e32 v128, v128
	v_cndmask_b32_e64 v186, 1.0, v129, s[6:7]
	v_cndmask_b32_e64 v187, 0, v128, s[6:7]
	v_add_u32_e32 v128, s35, v188
	v_mad_i64_i32 v[128:129], s[0:1], s86, v128, 0
	v_lshl_add_u64 v[132:133], v[128:129], 1, v[156:157]
	v_fma_f32 v128, s45, v189, v168
	v_cmp_gt_f32_e32 vcc, s85, v128
	v_mul_f32_e32 v129, 0x4b800000, v128
	s_mov_b64 s[0:1], -1
	v_cndmask_b32_e32 v128, v128, v129, vcc
	v_rsq_f32_e32 v128, v128
	s_nop 0
	v_mul_f32_e32 v129, 0x45800000, v128
	v_cndmask_b32_e32 v128, v128, v129, vcc
	v_mul_f32_e32 v130, v77, v128
	v_mul_f32_e32 v129, v76, v128
	v_mul_f32_e32 v130, v178, v130
	v_mul_f32_e32 v129, v179, v129
	v_mul_f32_e32 v131, v180, v130
	v_mul_f32_e32 v130, v135, v130
	v_mul_f32_e32 v188, v79, v128
	v_fma_f32 v131, v135, v129, -v131
	v_fmac_f32_e32 v130, v180, v129
	v_mul_f32_e32 v129, v78, v128
	v_mul_f32_e32 v188, v139, v188
	v_mul_f32_e32 v129, v177, v129
	v_mul_f32_e32 v189, v184, v188
	v_mul_f32_e32 v188, v181, v188
	v_mul_f32_e32 v190, v73, v128
	v_fma_f32 v189, v181, v129, -v189
	v_fmac_f32_e32 v188, v184, v129
	v_mul_f32_e32 v129, v72, v128
	v_mul_f32_e32 v190, v137, v190
	v_mul_f32_e32 v129, v138, v129
	v_mul_f32_e32 v191, v185, v190
	v_mul_f32_e32 v190, v183, v190
	v_fma_f32 v191, v183, v129, -v191
	v_fmac_f32_e32 v190, v185, v129
	v_mul_f32_e32 v129, v74, v128
	v_mul_f32_e32 v128, v75, v128
	v_mul_f32_e32 v128, v134, v128
	v_mul_f32_e32 v129, v136, v129
	v_mul_f32_e32 v192, v187, v128
	v_mul_f32_e32 v193, v186, v128
	v_cvt_pk_bf16_f32 v128, v131, v130
	v_fma_f32 v192, v186, v129, -v192
	v_fmac_f32_e32 v193, v187, v129
	v_cvt_pk_bf16_f32 v129, v189, v188
	v_cvt_pk_bf16_f32 v130, v191, v190
	v_cvt_pk_bf16_f32 v131, v192, v193
	global_store_dwordx4 v[132:133], v[128:131], off
	s_and_b64 vcc, exec, s[2:3]
	s_nop 0
	v_add_u32_e32 v128, s95, v182
	ds_read_b128 v[128:131], v128 offset:16
	s_cbranch_vccnz .LBB0_362
	s_and_b64 vcc, exec, s[4:5]
	s_cbranch_vccnz .LBB0_359
	s_waitcnt lgkmcnt(0)
	v_add_f32_e32 v182, v130, v131
	s_mov_b64 s[0:1], 0

; #define LAS __attribute__((address_space(3)))
;     __device__ __forceinline__ void operator()(const Acc& acc, const Unit& u, int wr, int wc, int fr_, int fq_) const {
;     ...
;             for (int m = 0; m < 4; ++m) { const int rt = ai * HALF + wr * 64 + m * 16 + fr;
;                 const int sp = (u.pm & 15) * BM + rt; const float pos = userow ? (float)(sp >> 6) : (float)(sp & 63);
;                 float cs[4], sn[4], ga[4], gb[4];
;                 { const float* gp = g + t0; asm volatile("" : "+v"(gp));
;                   const f32x4 g1 = *(const f32x4*)gp, g2 = *(const f32x4*)(gp + hd2);
; #pragma unroll
;                   for (int p = 0; p < 4; ++p) { ga[p] = g1[p] * osc; gb[p] = g2[p] * osc; } }
;     ...
;                 for (int bj = 0; bj < 2; ++bj) { const f32x4 xs = *(const LAS f32x4*)(X + (rt * 2 + bj) * 4);
;                     const float tot = h128 ? ((xs[0] + xs[1]) + (xs[2] + xs[3])) : ((wc & 2) ? (xs[2] + xs[3]) : (xs[0] + xs[1]));
;                     const float rstd = rsqrtf(tot * inv_w + EPS);
;                     const f32x4 v0 = acc[ai][bj][m][0], v1 = acc[ai][bj][m][1];
;                     float o[8]; const float e[8] = {v0[0], v0[1], v0[2], v0[3], v1[0], v1[1], v1[2], v1[3]};
; #pragma unroll
;                     for (int p = 0; p < 4; ++p) { const float x1 = e[2 * p] * rstd * ga[p], x2 = e[2 * p + 1] * rstd * gb[p];
;                         o[2 * p] = x1 * cs[p] - x2 * sn[p]; o[2 * p + 1] = x2 * cs[p] + x1 * sn[p]; }
;                     *(u32x4*)(rowp + bj * HALF) = pack8(o); }
.LBB0_364:
	s_waitcnt lgkmcnt(0)
	v_fma_f32 v128, s45, v182, v168
	v_cmp_gt_f32_e32 vcc, s85, v128
	v_mul_f32_e32 v129, 0x4b800000, v128
	s_nop 0
	v_cndmask_b32_e32 v128, v128, v129, vcc
	v_rsq_f32_e32 v128, v128
	s_nop 0
	v_mul_f32_e32 v129, 0x45800000, v128
	v_cndmask_b32_e32 v128, v128, v129, vcc
	v_mul_f32_e32 v130, v69, v128
	v_mul_f32_e32 v129, v68, v128
	v_mul_f32_e32 v130, v178, v130
	v_mul_f32_e32 v129, v179, v129
	v_mul_f32_e32 v131, v180, v130
	v_fma_f32 v131, v135, v129, -v131
	v_mul_f32_e32 v130, v135, v130
	v_mul_f32_e32 v135, v71, v128
	v_fmac_f32_e32 v130, v180, v129
	v_mul_f32_e32 v129, v70, v128
	v_mul_f32_e32 v135, v139, v135
	v_mul_f32_e32 v129, v177, v129
	v_mul_f32_e32 v139, v184, v135
	v_mul_f32_e32 v135, v181, v135
	v_fma_f32 v139, v181, v129, -v139
	v_fmac_f32_e32 v135, v184, v129
	v_mul_f32_e32 v129, v64, v128
	v_mul_f32_e32 v129, v138, v129
	v_mul_f32_e32 v138, v65, v128
	v_mul_f32_e32 v137, v137, v138
	v_mul_f32_e32 v138, v185, v137
	v_mul_f32_e32 v137, v183, v137
	v_fma_f32 v138, v183, v129, -v138
	v_fmac_f32_e32 v137, v185, v129
	v_mul_f32_e32 v129, v66, v128
	v_mul_f32_e32 v128, v67, v128
	v_mul_f32_e32 v128, v134, v128
	v_mul_f32_e32 v129, v136, v129
	v_mul_f32_e32 v134, v187, v128
	v_mul_f32_e32 v136, v186, v128
	v_fma_f32 v134, v186, v129, -v134
	v_fmac_f32_e32 v136, v187, v129
	v_cvt_pk_bf16_f32 v128, v131, v130
	v_cvt_pk_bf16_f32 v129, v139, v135
	v_cvt_pk_bf16_f32 v130, v138, v137
	v_cvt_pk_bf16_f32 v131, v134, v136
	global_store_dwordx4 v[132:133], v[128:131], off offset:256
	s_nop 1
	v_mov_b64_e32 v[128:129], v[158:159]
	v_add_u32_e32 v187, 0x80, v171
	v_lshl_add_u64 v[132:133], v[128:129], 0, s[22:23]
	v_mov_b32_e32 v128, v194
	v_mov_b32_e32 v129, v195
	v_mov_b32_e32 v130, v196
	v_mov_b32_e32 v131, v197
	v_mov_b32_e32 v132, v198
	v_mov_b32_e32 v133, v199
	v_mov_b32_e32 v134, v200
	v_mov_b32_e32 v135, v201
	v_lshlrev_b32_e32 v181, 5, v187
	v_add_u32_e32 v136, 0, v181
	v_add_u32_e32 v136, 0x20000, v136
	ds_read_b128 v[136:139], v136
	s_and_b64 vcc, exec, s[2:3]
	s_mov_b64 s[0:1], -1
	s_cbranch_vccnz .LBB0_370
	s_and_b64 vcc, exec, s[4:5]
	s_cbranch_vccnz .LBB0_367
	s_waitcnt lgkmcnt(0)
	v_add_f32_e32 v188, v138, v139
	s_mov_b64 s[0:1], 0

; #define LAS __attribute__((address_space(3)))
;     __device__ __forceinline__ void operator()(const Acc& acc, const Unit& u, int wr, int wc, int fr_, int fq_) const {
;     ...
;             for (int m = 0; m < 4; ++m) { const int rt = ai * HALF + wr * 64 + m * 16 + fr;
;                 const int sp = (u.pm & 15) * BM + rt; const float pos = userow ? (float)(sp >> 6) : (float)(sp & 63);
;                 float cs[4], sn[4], ga[4], gb[4];
;                 { const float* gp = g + t0; asm volatile("" : "+v"(gp));
;                   const f32x4 g1 = *(const f32x4*)gp, g2 = *(const f32x4*)(gp + hd2);
; #pragma unroll
;                   for (int p = 0; p < 4; ++p) { ga[p] = g1[p] * osc; gb[p] = g2[p] * osc; } }
; #pragma unroll
;                 for (int p = 0; p < 4; ++p) { const float ang = pos * __builtin_amdgcn_exp2f(-(float)((t0 + p) & (nf - 1)) * (13.287712379549449f / (float)nf));
;                     cs[p] = rope ? __cosf(ang) : 1.f; sn[p] = rope ? __sinf(ang) : 0.f; }
;                 bf16_t* rowp = base + (size_t)(rowbase + rt) * ld + col0;
; #pragma unroll
;                 for (int bj = 0; bj < 2; ++bj) { const f32x4 xs = *(const LAS f32x4*)(X + (rt * 2 + bj) * 4);
;                     const float tot = h128 ? ((xs[0] + xs[1]) + (xs[2] + xs[3])) : ((wc & 2) ? (xs[2] + xs[3]) : (xs[0] + xs[1]));
;                     const float rstd = rsqrtf(tot * inv_w + EPS);
;                     const f32x4 v0 = acc[ai][bj][m][0], v1 = acc[ai][bj][m][1];
;                     float o[8]; const float e[8] = {v0[0], v0[1], v0[2], v0[3], v1[0], v1[1], v1[2], v1[3]};
; #pragma unroll
;                     for (int p = 0; p < 4; ++p) { const float x1 = e[2 * p] * rstd * ga[p], x2 = e[2 * p + 1] * rstd * gb[p];
;                         o[2 * p] = x1 * cs[p] - x2 * sn[p]; o[2 * p + 1] = x2 * cs[p] + x1 * sn[p]; }
;                     *(u32x4*)(rowp + bj * HALF) = pack8(o); }
.LBB0_372:
	s_waitcnt lgkmcnt(0)
	v_add_u32_e32 v136, s87, v187
	v_ashrrev_i32_e32 v136, 6, v136
	v_cvt_f32_i32_e32 v136, v136
	s_nop 0
	v_mul_f32_e32 v178, s43, v128
	v_mul_f32_e32 v139, s43, v129
	v_mul_f32_e32 v137, s43, v134
	v_cndmask_b32_e64 v185, v173, v136, s[8:9]
	v_mul_f32_e32 v128, v185, v155
	v_mul_f32_e32 v128, 0.15915494, v128
	v_cos_f32_e32 v129, v128
	v_sin_f32_e32 v128, v128
	v_mul_f32_e32 v134, s43, v135
	v_mul_f32_e32 v177, s43, v132
	v_cndmask_b32_e64 v135, 1.0, v129, s[6:7]
	v_cndmask_b32_e64 v179, 0, v128, s[6:7]
	v_mul_f32_e32 v128, v185, v161
	v_mul_f32_e32 v128, 0.15915494, v128
	v_cos_f32_e32 v129, v128
	v_sin_f32_e32 v128, v128
	v_mul_f32_e32 v173, s43, v133
	v_mul_f32_e32 v138, s43, v130
	v_cndmask_b32_e64 v180, 1.0, v129, s[6:7]
	v_cndmask_b32_e64 v183, 0, v128, s[6:7]
	v_mul_f32_e32 v128, v185, v172
	v_mul_f32_e32 v128, 0.15915494, v128
	v_cos_f32_e32 v129, v128
	v_sin_f32_e32 v128, v128
	v_mul_f32_e32 v136, s43, v131
	v_cndmask_b32_e64 v182, 1.0, v129, s[6:7]
	v_cndmask_b32_e64 v184, 0, v128, s[6:7]
	v_mul_f32_e32 v128, v185, v160
	v_mul_f32_e32 v128, 0.15915494, v128
	v_cos_f32_e32 v129, v128
	v_sin_f32_e32 v128, v128
	v_cndmask_b32_e64 v185, 1.0, v129, s[6:7]
	v_cndmask_b32_e64 v186, 0, v128, s[6:7]
	v_add_u32_e32 v128, s35, v187
	v_mad_i64_i32 v[128:129], s[0:1], s86, v128, 0
	v_lshl_add_u64 v[132:133], v[128:129], 1, v[156:157]
	v_fma_f32 v128, s45, v188, v168
	v_cmp_gt_f32_e32 vcc, s85, v128
	v_mul_f32_e32 v129, 0x4b800000, v128
	s_mov_b64 s[0:1], -1
	v_cndmask_b32_e32 v128, v128, v129, vcc
	v_rsq_f32_e32 v128, v128
	s_nop 0
	v_mul_f32_e32 v129, 0x45800000, v128
	v_cndmask_b32_e32 v128, v128, v129, vcc
	v_mul_f32_e32 v130, v61, v128
	v_mul_f32_e32 v129, v60, v128
	v_mul_f32_e32 v130, v177, v130
	v_mul_f32_e32 v129, v178, v129
	v_mul_f32_e32 v131, v179, v130
	v_mul_f32_e32 v130, v135, v130
	v_mul_f32_e32 v187, v63, v128
	v_fma_f32 v131, v135, v129, -v131
	v_fmac_f32_e32 v130, v179, v129
	v_mul_f32_e32 v129, v62, v128
	v_mul_f32_e32 v187, v173, v187
	v_mul_f32_e32 v129, v139, v129
	v_mul_f32_e32 v188, v183, v187
	v_mul_f32_e32 v187, v180, v187
	v_mul_f32_e32 v189, v57, v128
	v_fma_f32 v188, v180, v129, -v188
	v_fmac_f32_e32 v187, v183, v129
	v_mul_f32_e32 v129, v56, v128
	v_mul_f32_e32 v189, v137, v189
	v_mul_f32_e32 v129, v138, v129
	v_mul_f32_e32 v190, v184, v189
	v_mul_f32_e32 v189, v182, v189
	v_fma_f32 v190, v182, v129, -v190
	v_fmac_f32_e32 v189, v184, v129
	v_mul_f32_e32 v129, v58, v128
	v_mul_f32_e32 v128, v59, v128
	v_mul_f32_e32 v128, v134, v128
	v_mul_f32_e32 v129, v136, v129
	v_mul_f32_e32 v191, v186, v128
	v_mul_f32_e32 v192, v185, v128
	v_cvt_pk_bf16_f32 v128, v131, v130
	v_fma_f32 v191, v185, v129, -v191
	v_fmac_f32_e32 v192, v186, v129
	v_cvt_pk_bf16_f32 v129, v188, v187
	v_cvt_pk_bf16_f32 v130, v190, v189
	v_cvt_pk_bf16_f32 v131, v191, v192
	global_store_dwordx4 v[132:133], v[128:131], off
	s_and_b64 vcc, exec, s[2:3]
	s_nop 0
	v_add_u32_e32 v128, s95, v181
	ds_read_b128 v[128:131], v128 offset:16
	s_cbranch_vccnz .LBB0_378
	s_and_b64 vcc, exec, s[4:5]
	s_cbranch_vccnz .LBB0_375
	s_waitcnt lgkmcnt(0)
	v_add_f32_e32 v181, v130, v131
	s_mov_b64 s[0:1], 0

; #define LAS __attribute__((address_space(3)))
;     __device__ __forceinline__ void operator()(const Acc& acc, const Unit& u, int wr, int wc, int fr_, int fq_) const {
;     ...
;             for (int m = 0; m < 4; ++m) { const int rt = ai * HALF + wr * 64 + m * 16 + fr;
;                 const int sp = (u.pm & 15) * BM + rt; const float pos = userow ? (float)(sp >> 6) : (float)(sp & 63);
;                 float cs[4], sn[4], ga[4], gb[4];
;                 { const float* gp = g + t0; asm volatile("" : "+v"(gp));
;                   const f32x4 g1 = *(const f32x4*)gp, g2 = *(const f32x4*)(gp + hd2);
; #pragma unroll
;                   for (int p = 0; p < 4; ++p) { ga[p] = g1[p] * osc; gb[p] = g2[p] * osc; } }
;     ...
;                 for (int bj = 0; bj < 2; ++bj) { const f32x4 xs = *(const LAS f32x4*)(X + (rt * 2 + bj) * 4);
;                     const float tot = h128 ? ((xs[0] + xs[1]) + (xs[2] + xs[3])) : ((wc & 2) ? (xs[2] + xs[3]) : (xs[0] + xs[1]));
;                     const float rstd = rsqrtf(tot * inv_w + EPS);
;                     const f32x4 v0 = acc[ai][bj][m][0], v1 = acc[ai][bj][m][1];
;                     float o[8]; const float e[8] = {v0[0], v0[1], v0[2], v0[3], v1[0], v1[1], v1[2], v1[3]};
; #pragma unroll
;                     for (int p = 0; p < 4; ++p) { const float x1 = e[2 * p] * rstd * ga[p], x2 = e[2 * p + 1] * rstd * gb[p];
;                         o[2 * p] = x1 * cs[p] - x2 * sn[p]; o[2 * p + 1] = x2 * cs[p] + x1 * sn[p]; }
;                     *(u32x4*)(rowp + bj * HALF) = pack8(o); }
.LBB0_380:
	s_waitcnt lgkmcnt(0)
	v_fma_f32 v128, s45, v181, v168
	v_cmp_gt_f32_e32 vcc, s85, v128
	v_mul_f32_e32 v129, 0x4b800000, v128
	s_nop 0
	v_cndmask_b32_e32 v128, v128, v129, vcc
	v_rsq_f32_e32 v128, v128
	s_nop 0
	v_mul_f32_e32 v129, 0x45800000, v128
	v_cndmask_b32_e32 v128, v128, v129, vcc
	v_mul_f32_e32 v130, v53, v128
	v_mul_f32_e32 v129, v52, v128
	v_mul_f32_e32 v130, v177, v130
	v_mul_f32_e32 v129, v178, v129
	v_mul_f32_e32 v131, v179, v130
	v_fma_f32 v131, v135, v129, -v131
	v_mul_f32_e32 v130, v135, v130
	v_mul_f32_e32 v135, v55, v128
	v_fmac_f32_e32 v130, v179, v129
	v_mul_f32_e32 v129, v54, v128
	v_mul_f32_e32 v135, v173, v135
	v_mul_f32_e32 v129, v139, v129
	v_mul_f32_e32 v139, v183, v135
	v_mul_f32_e32 v135, v180, v135
	v_fma_f32 v139, v180, v129, -v139
	v_fmac_f32_e32 v135, v183, v129
	v_mul_f32_e32 v129, v48, v128
	v_mul_f32_e32 v129, v138, v129
	v_mul_f32_e32 v138, v49, v128
	v_mul_f32_e32 v137, v137, v138
	v_mul_f32_e32 v138, v184, v137
	v_mul_f32_e32 v137, v182, v137
	v_fma_f32 v138, v182, v129, -v138
	v_fmac_f32_e32 v137, v184, v129
	v_mul_f32_e32 v129, v50, v128
	v_mul_f32_e32 v128, v51, v128
	v_mul_f32_e32 v128, v134, v128
	v_mul_f32_e32 v129, v136, v129
	v_mul_f32_e32 v134, v186, v128
	v_mul_f32_e32 v136, v185, v128
	v_fma_f32 v134, v185, v129, -v134
	v_fmac_f32_e32 v136, v186, v129
	v_cvt_pk_bf16_f32 v128, v131, v130
	v_cvt_pk_bf16_f32 v129, v139, v135
	v_cvt_pk_bf16_f32 v130, v138, v137
	v_cvt_pk_bf16_f32 v131, v134, v136
	global_store_dwordx4 v[132:133], v[128:131], off offset:256
	s_nop 1
	v_mov_b64_e32 v[128:129], v[158:159]
	v_add_u32_e32 v186, 0x90, v171
	v_lshl_add_u64 v[132:133], v[128:129], 0, s[22:23]
	v_mov_b32_e32 v128, v194
	v_mov_b32_e32 v129, v195
	v_mov_b32_e32 v130, v196
	v_mov_b32_e32 v131, v197
	v_mov_b32_e32 v132, v198
	v_mov_b32_e32 v133, v199
	v_mov_b32_e32 v134, v200
	v_mov_b32_e32 v135, v201
	v_lshlrev_b32_e32 v180, 5, v186
	v_add_u32_e32 v136, 0, v180
	v_add_u32_e32 v136, 0x20000, v136
	ds_read_b128 v[136:139], v136
	s_and_b64 vcc, exec, s[2:3]
	s_mov_b64 s[0:1], -1
	s_cbranch_vccnz .LBB0_386
	s_and_b64 vcc, exec, s[4:5]
	s_cbranch_vccnz .LBB0_383
	s_waitcnt lgkmcnt(0)
	v_add_f32_e32 v187, v138, v139
	s_mov_b64 s[0:1], 0

; #define LAS __attribute__((address_space(3)))
;     __device__ __forceinline__ void operator()(const Acc& acc, const Unit& u, int wr, int wc, int fr_, int fq_) const {
;     ...
;             for (int m = 0; m < 4; ++m) { const int rt = ai * HALF + wr * 64 + m * 16 + fr;
;                 const int sp = (u.pm & 15) * BM + rt; const float pos = userow ? (float)(sp >> 6) : (float)(sp & 63);
;                 float cs[4], sn[4], ga[4], gb[4];
;                 { const float* gp = g + t0; asm volatile("" : "+v"(gp));
;                   const f32x4 g1 = *(const f32x4*)gp, g2 = *(const f32x4*)(gp + hd2);
; #pragma unroll
;                   for (int p = 0; p < 4; ++p) { ga[p] = g1[p] * osc; gb[p] = g2[p] * osc; } }
; #pragma unroll
;                 for (int p = 0; p < 4; ++p) { const float ang = pos * __builtin_amdgcn_exp2f(-(float)((t0 + p) & (nf - 1)) * (13.287712379549449f / (float)nf));
;                     cs[p] = rope ? __cosf(ang) : 1.f; sn[p] = rope ? __sinf(ang) : 0.f; }
;                 bf16_t* rowp = base + (size_t)(rowbase + rt) * ld + col0;
; #pragma unroll
;                 for (int bj = 0; bj < 2; ++bj) { const f32x4 xs = *(const LAS f32x4*)(X + (rt * 2 + bj) * 4);
;                     const float tot = h128 ? ((xs[0] + xs[1]) + (xs[2] + xs[3])) : ((wc & 2) ? (xs[2] + xs[3]) : (xs[0] + xs[1]));
;                     const float rstd = rsqrtf(tot * inv_w + EPS);
;                     const f32x4 v0 = acc[ai][bj][m][0], v1 = acc[ai][bj][m][1];
;                     float o[8]; const float e[8] = {v0[0], v0[1], v0[2], v0[3], v1[0], v1[1], v1[2], v1[3]};
; #pragma unroll
;                     for (int p = 0; p < 4; ++p) { const float x1 = e[2 * p] * rstd * ga[p], x2 = e[2 * p + 1] * rstd * gb[p];
;                         o[2 * p] = x1 * cs[p] - x2 * sn[p]; o[2 * p + 1] = x2 * cs[p] + x1 * sn[p]; }
;                     *(u32x4*)(rowp + bj * HALF) = pack8(o); }
.LBB0_388:
	s_waitcnt lgkmcnt(0)
	v_add_u32_e32 v136, s87, v186
	v_ashrrev_i32_e32 v136, 6, v136
	v_cvt_f32_i32_e32 v136, v136
	s_nop 0
	v_mul_f32_e32 v177, s43, v128
	v_mul_f32_e32 v139, s43, v129
	v_mul_f32_e32 v137, s43, v134
	v_cndmask_b32_e64 v184, v175, v136, s[8:9]
	v_mul_f32_e32 v128, v184, v155
	v_mul_f32_e32 v128, 0.15915494, v128
	v_cos_f32_e32 v129, v128
	v_sin_f32_e32 v128, v128
	v_mul_f32_e32 v134, s43, v135
	v_mul_f32_e32 v175, s43, v132
	v_cndmask_b32_e64 v135, 1.0, v129, s[6:7]
	v_cndmask_b32_e64 v178, 0, v128, s[6:7]
	v_mul_f32_e32 v128, v184, v161
	v_mul_f32_e32 v128, 0.15915494, v128
	v_cos_f32_e32 v129, v128
	v_sin_f32_e32 v128, v128
	v_mul_f32_e32 v173, s43, v133
	v_mul_f32_e32 v138, s43, v130
	v_cndmask_b32_e64 v179, 1.0, v129, s[6:7]
	v_cndmask_b32_e64 v182, 0, v128, s[6:7]
	v_mul_f32_e32 v128, v184, v172
	v_mul_f32_e32 v128, 0.15915494, v128
	v_cos_f32_e32 v129, v128
	v_sin_f32_e32 v128, v128
	v_mul_f32_e32 v136, s43, v131
	v_cndmask_b32_e64 v181, 1.0, v129, s[6:7]
	v_cndmask_b32_e64 v183, 0, v128, s[6:7]
	v_mul_f32_e32 v128, v184, v160
	v_mul_f32_e32 v128, 0.15915494, v128
	v_cos_f32_e32 v129, v128
	v_sin_f32_e32 v128, v128
	v_cndmask_b32_e64 v184, 1.0, v129, s[6:7]
	v_cndmask_b32_e64 v185, 0, v128, s[6:7]
	v_add_u32_e32 v128, s35, v186
	v_mad_i64_i32 v[128:129], s[0:1], s86, v128, 0
	v_lshl_add_u64 v[132:133], v[128:129], 1, v[156:157]
	v_fma_f32 v128, s45, v187, v168
	v_cmp_gt_f32_e32 vcc, s85, v128
	v_mul_f32_e32 v129, 0x4b800000, v128
	s_mov_b64 s[0:1], -1
	v_cndmask_b32_e32 v128, v128, v129, vcc
	v_rsq_f32_e32 v128, v128
	s_nop 0
	v_mul_f32_e32 v129, 0x45800000, v128
	v_cndmask_b32_e32 v128, v128, v129, vcc
	v_mul_f32_e32 v130, v45, v128
	v_mul_f32_e32 v129, v44, v128
	v_mul_f32_e32 v130, v175, v130
	v_mul_f32_e32 v129, v177, v129
	v_mul_f32_e32 v131, v178, v130
	v_mul_f32_e32 v130, v135, v130
	v_mul_f32_e32 v186, v47, v128
	v_fma_f32 v131, v135, v129, -v131
	v_fmac_f32_e32 v130, v178, v129
	v_mul_f32_e32 v129, v46, v128
	v_mul_f32_e32 v186, v173, v186
	v_mul_f32_e32 v129, v139, v129
	v_mul_f32_e32 v187, v182, v186
	v_mul_f32_e32 v186, v179, v186
	v_mul_f32_e32 v188, v41, v128
	v_fma_f32 v187, v179, v129, -v187
	v_fmac_f32_e32 v186, v182, v129
	v_mul_f32_e32 v129, v40, v128
	v_mul_f32_e32 v188, v137, v188
	v_mul_f32_e32 v129, v138, v129
	v_mul_f32_e32 v189, v183, v188
	v_mul_f32_e32 v188, v181, v188
	v_fma_f32 v189, v181, v129, -v189
	v_fmac_f32_e32 v188, v183, v129
	v_mul_f32_e32 v129, v42, v128
	v_mul_f32_e32 v128, v43, v128
	v_mul_f32_e32 v128, v134, v128
	v_mul_f32_e32 v129, v136, v129
	v_mul_f32_e32 v190, v185, v128
	v_mul_f32_e32 v191, v184, v128
	v_cvt_pk_bf16_f32 v128, v131, v130
	v_fma_f32 v190, v184, v129, -v190
	v_fmac_f32_e32 v191, v185, v129
	v_cvt_pk_bf16_f32 v129, v187, v186
	v_cvt_pk_bf16_f32 v130, v189, v188
	v_cvt_pk_bf16_f32 v131, v190, v191
	global_store_dwordx4 v[132:133], v[128:131], off
	s_and_b64 vcc, exec, s[2:3]
	s_nop 0
	v_add_u32_e32 v128, s95, v180
	ds_read_b128 v[128:131], v128 offset:16
	s_cbranch_vccnz .LBB0_394
	s_and_b64 vcc, exec, s[4:5]
	s_cbranch_vccnz .LBB0_391
	s_waitcnt lgkmcnt(0)
	v_add_f32_e32 v180, v130, v131
	s_mov_b64 s[0:1], 0

; #define LAS __attribute__((address_space(3)))
;     __device__ __forceinline__ void operator()(const Acc& acc, const Unit& u, int wr, int wc, int fr_, int fq_) const {
;     ...
;             for (int m = 0; m < 4; ++m) { const int rt = ai * HALF + wr * 64 + m * 16 + fr;
;                 const int sp = (u.pm & 15) * BM + rt; const float pos = userow ? (float)(sp >> 6) : (float)(sp & 63);
;                 float cs[4], sn[4], ga[4], gb[4];
;                 { const float* gp = g + t0; asm volatile("" : "+v"(gp));
;                   const f32x4 g1 = *(const f32x4*)gp, g2 = *(const f32x4*)(gp + hd2);
; #pragma unroll
;                   for (int p = 0; p < 4; ++p) { ga[p] = g1[p] * osc; gb[p] = g2[p] * osc; } }
;     ...
;                 for (int bj = 0; bj < 2; ++bj) { const f32x4 xs = *(const LAS f32x4*)(X + (rt * 2 + bj) * 4);
;                     const float tot = h128 ? ((xs[0] + xs[1]) + (xs[2] + xs[3])) : ((wc & 2) ? (xs[2] + xs[3]) : (xs[0] + xs[1]));
;                     const float rstd = rsqrtf(tot * inv_w + EPS);
;                     const f32x4 v0 = acc[ai][bj][m][0], v1 = acc[ai][bj][m][1];
;                     float o[8]; const float e[8] = {v0[0], v0[1], v0[2], v0[3], v1[0], v1[1], v1[2], v1[3]};
; #pragma unroll
;                     for (int p = 0; p < 4; ++p) { const float x1 = e[2 * p] * rstd * ga[p], x2 = e[2 * p + 1] * rstd * gb[p];
;                         o[2 * p] = x1 * cs[p] - x2 * sn[p]; o[2 * p + 1] = x2 * cs[p] + x1 * sn[p]; }
;                     *(u32x4*)(rowp + bj * HALF) = pack8(o); }
.LBB0_396:
	s_waitcnt lgkmcnt(0)
	v_fma_f32 v128, s45, v180, v168
	v_cmp_gt_f32_e32 vcc, s85, v128
	v_mul_f32_e32 v129, 0x4b800000, v128
	s_nop 0
	v_cndmask_b32_e32 v128, v128, v129, vcc
	v_rsq_f32_e32 v128, v128
	s_nop 0
	v_mul_f32_e32 v129, 0x45800000, v128
	v_cndmask_b32_e32 v128, v128, v129, vcc
	v_mul_f32_e32 v130, v37, v128
	v_mul_f32_e32 v129, v36, v128
	v_mul_f32_e32 v130, v175, v130
	v_mul_f32_e32 v129, v177, v129
	v_mul_f32_e32 v131, v178, v130
	v_fma_f32 v131, v135, v129, -v131
	v_mul_f32_e32 v130, v135, v130
	v_mul_f32_e32 v135, v39, v128
	v_fmac_f32_e32 v130, v178, v129
	v_mul_f32_e32 v129, v38, v128
	v_mul_f32_e32 v135, v173, v135
	v_mul_f32_e32 v129, v139, v129
	v_mul_f32_e32 v139, v182, v135
	v_mul_f32_e32 v135, v179, v135
	v_fma_f32 v139, v179, v129, -v139
	v_fmac_f32_e32 v135, v182, v129
	v_mul_f32_e32 v129, v32, v128
	v_mul_f32_e32 v129, v138, v129
	v_mul_f32_e32 v138, v33, v128
	v_mul_f32_e32 v137, v137, v138
	v_mul_f32_e32 v138, v183, v137
	v_mul_f32_e32 v137, v181, v137
	v_fma_f32 v138, v181, v129, -v138
	v_fmac_f32_e32 v137, v183, v129
	v_mul_f32_e32 v129, v34, v128
	v_mul_f32_e32 v128, v35, v128
	v_mul_f32_e32 v128, v134, v128
	v_mul_f32_e32 v129, v136, v129
	v_mul_f32_e32 v134, v185, v128
	v_mul_f32_e32 v136, v184, v128
	v_fma_f32 v134, v184, v129, -v134
	v_fmac_f32_e32 v136, v185, v129
	v_cvt_pk_bf16_f32 v128, v131, v130
	v_cvt_pk_bf16_f32 v129, v139, v135
	v_cvt_pk_bf16_f32 v130, v138, v137
	v_cvt_pk_bf16_f32 v131, v134, v136
	global_store_dwordx4 v[132:133], v[128:131], off offset:256
	s_nop 1
	v_mov_b64_e32 v[128:129], v[158:159]
	v_add_u32_e32 v185, 0xa0, v171
	v_lshl_add_u64 v[132:133], v[128:129], 0, s[22:23]
	v_mov_b32_e32 v128, v194
	v_mov_b32_e32 v129, v195
	v_mov_b32_e32 v130, v196
	v_mov_b32_e32 v131, v197
	v_mov_b32_e32 v132, v198
	v_mov_b32_e32 v133, v199
	v_mov_b32_e32 v134, v200
	v_mov_b32_e32 v135, v201
	v_lshlrev_b32_e32 v179, 5, v185
	v_add_u32_e32 v136, 0, v179
	v_add_u32_e32 v136, 0x20000, v136
	ds_read_b128 v[136:139], v136
	s_and_b64 vcc, exec, s[2:3]
	s_mov_b64 s[0:1], -1
	s_cbranch_vccnz .LBB0_402
	s_and_b64 vcc, exec, s[4:5]
	s_cbranch_vccnz .LBB0_399
	s_waitcnt lgkmcnt(0)
	v_add_f32_e32 v186, v138, v139
	s_mov_b64 s[0:1], 0

; #define LAS __attribute__((address_space(3)))
;     __device__ __forceinline__ void operator()(const Acc& acc, const Unit& u, int wr, int wc, int fr_, int fq_) const {
;     ...
;             for (int m = 0; m < 4; ++m) { const int rt = ai * HALF + wr * 64 + m * 16 + fr;
;                 const int sp = (u.pm & 15) * BM + rt; const float pos = userow ? (float)(sp >> 6) : (float)(sp & 63);
;                 float cs[4], sn[4], ga[4], gb[4];
;                 { const float* gp = g + t0; asm volatile("" : "+v"(gp));
;                   const f32x4 g1 = *(const f32x4*)gp, g2 = *(const f32x4*)(gp + hd2);
; #pragma unroll
;                   for (int p = 0; p < 4; ++p) { ga[p] = g1[p] * osc; gb[p] = g2[p] * osc; } }
; #pragma unroll
;                 for (int p = 0; p < 4; ++p) { const float ang = pos * __builtin_amdgcn_exp2f(-(float)((t0 + p) & (nf - 1)) * (13.287712379549449f / (float)nf));
;                     cs[p] = rope ? __cosf(ang) : 1.f; sn[p] = rope ? __sinf(ang) : 0.f; }
;                 bf16_t* rowp = base + (size_t)(rowbase + rt) * ld + col0;
; #pragma unroll
;                 for (int bj = 0; bj < 2; ++bj) { const f32x4 xs = *(const LAS f32x4*)(X + (rt * 2 + bj) * 4);
;                     const float tot = h128 ? ((xs[0] + xs[1]) + (xs[2] + xs[3])) : ((wc & 2) ? (xs[2] + xs[3]) : (xs[0] + xs[1]));
;                     const float rstd = rsqrtf(tot * inv_w + EPS);
;                     const f32x4 v0 = acc[ai][bj][m][0], v1 = acc[ai][bj][m][1];
;                     float o[8]; const float e[8] = {v0[0], v0[1], v0[2], v0[3], v1[0], v1[1], v1[2], v1[3]};
; #pragma unroll
;                     for (int p = 0; p < 4; ++p) { const float x1 = e[2 * p] * rstd * ga[p], x2 = e[2 * p + 1] * rstd * gb[p];
;                         o[2 * p] = x1 * cs[p] - x2 * sn[p]; o[2 * p + 1] = x2 * cs[p] + x1 * sn[p]; }
;                     *(u32x4*)(rowp + bj * HALF) = pack8(o); }
.LBB0_404:
	s_waitcnt lgkmcnt(0)
	v_add_u32_e32 v136, s87, v185
	v_ashrrev_i32_e32 v136, 6, v136
	v_cvt_f32_i32_e32 v136, v136
	s_nop 0
	v_mul_f32_e32 v175, s43, v128
	v_mul_f32_e32 v139, s43, v129
	v_mul_f32_e32 v137, s43, v134
	v_cndmask_b32_e64 v183, v174, v136, s[8:9]
	v_mul_f32_e32 v128, v183, v155
	v_mul_f32_e32 v128, 0.15915494, v128
	v_cos_f32_e32 v129, v128
	v_sin_f32_e32 v128, v128
	v_mul_f32_e32 v134, s43, v135
	v_mul_f32_e32 v174, s43, v132
	v_cndmask_b32_e64 v135, 1.0, v129, s[6:7]
	v_cndmask_b32_e64 v177, 0, v128, s[6:7]
	v_mul_f32_e32 v128, v183, v161
	v_mul_f32_e32 v128, 0.15915494, v128
	v_cos_f32_e32 v129, v128
	v_sin_f32_e32 v128, v128
	v_mul_f32_e32 v173, s43, v133
	v_mul_f32_e32 v138, s43, v130
	v_cndmask_b32_e64 v178, 1.0, v129, s[6:7]
	v_cndmask_b32_e64 v181, 0, v128, s[6:7]
	v_mul_f32_e32 v128, v183, v172
	v_mul_f32_e32 v128, 0.15915494, v128
	v_cos_f32_e32 v129, v128
	v_sin_f32_e32 v128, v128
	v_mul_f32_e32 v136, s43, v131
	v_cndmask_b32_e64 v180, 1.0, v129, s[6:7]
	v_cndmask_b32_e64 v182, 0, v128, s[6:7]
	v_mul_f32_e32 v128, v183, v160
	v_mul_f32_e32 v128, 0.15915494, v128
	v_cos_f32_e32 v129, v128
	v_sin_f32_e32 v128, v128
	v_cndmask_b32_e64 v183, 1.0, v129, s[6:7]
	v_cndmask_b32_e64 v184, 0, v128, s[6:7]
	v_add_u32_e32 v128, s35, v185
	v_mad_i64_i32 v[128:129], s[0:1], s86, v128, 0
	v_lshl_add_u64 v[132:133], v[128:129], 1, v[156:157]
	v_fma_f32 v128, s45, v186, v168
	v_cmp_gt_f32_e32 vcc, s85, v128
	v_mul_f32_e32 v129, 0x4b800000, v128
	s_mov_b64 s[0:1], -1
	v_cndmask_b32_e32 v128, v128, v129, vcc
	v_rsq_f32_e32 v128, v128
	s_nop 0
	v_mul_f32_e32 v129, 0x45800000, v128
	v_cndmask_b32_e32 v128, v128, v129, vcc
	v_mul_f32_e32 v130, v29, v128
	v_mul_f32_e32 v129, v28, v128
	v_mul_f32_e32 v130, v174, v130
	v_mul_f32_e32 v129, v175, v129
	v_mul_f32_e32 v131, v177, v130
	v_mul_f32_e32 v130, v135, v130
	v_mul_f32_e32 v185, v31, v128
	v_fma_f32 v131, v135, v129, -v131
	v_fmac_f32_e32 v130, v177, v129
	v_mul_f32_e32 v129, v30, v128
	v_mul_f32_e32 v185, v173, v185
	v_mul_f32_e32 v129, v139, v129
	v_mul_f32_e32 v186, v181, v185
	v_mul_f32_e32 v185, v178, v185
	v_mul_f32_e32 v187, v25, v128
	v_fma_f32 v186, v178, v129, -v186
	v_fmac_f32_e32 v185, v181, v129
	v_mul_f32_e32 v129, v24, v128
	v_mul_f32_e32 v187, v137, v187
	v_mul_f32_e32 v129, v138, v129
	v_mul_f32_e32 v188, v182, v187
	v_mul_f32_e32 v187, v180, v187
	v_fma_f32 v188, v180, v129, -v188
	v_fmac_f32_e32 v187, v182, v129
	v_mul_f32_e32 v129, v26, v128
	v_mul_f32_e32 v128, v27, v128
	v_mul_f32_e32 v128, v134, v128
	v_mul_f32_e32 v129, v136, v129
	v_mul_f32_e32 v189, v184, v128
	v_mul_f32_e32 v190, v183, v128
	v_cvt_pk_bf16_f32 v128, v131, v130
	v_fma_f32 v189, v183, v129, -v189
	v_fmac_f32_e32 v190, v184, v129
	v_cvt_pk_bf16_f32 v129, v186, v185
	v_cvt_pk_bf16_f32 v130, v188, v187
	v_cvt_pk_bf16_f32 v131, v189, v190
	global_store_dwordx4 v[132:133], v[128:131], off
	s_and_b64 vcc, exec, s[2:3]
	s_nop 0
	v_add_u32_e32 v128, s95, v179
	ds_read_b128 v[128:131], v128 offset:16
	s_cbranch_vccnz .LBB0_410
	s_and_b64 vcc, exec, s[4:5]
	s_cbranch_vccnz .LBB0_407
	s_waitcnt lgkmcnt(0)
	v_add_f32_e32 v179, v130, v131
	s_mov_b64 s[0:1], 0

; #define LAS __attribute__((address_space(3)))
;     __device__ __forceinline__ void operator()(const Acc& acc, const Unit& u, int wr, int wc, int fr_, int fq_) const {
;     ...
;             for (int m = 0; m < 4; ++m) { const int rt = ai * HALF + wr * 64 + m * 16 + fr;
;                 const int sp = (u.pm & 15) * BM + rt; const float pos = userow ? (float)(sp >> 6) : (float)(sp & 63);
;                 float cs[4], sn[4], ga[4], gb[4];
;                 { const float* gp = g + t0; asm volatile("" : "+v"(gp));
;                   const f32x4 g1 = *(const f32x4*)gp, g2 = *(const f32x4*)(gp + hd2);
; #pragma unroll
;                   for (int p = 0; p < 4; ++p) { ga[p] = g1[p] * osc; gb[p] = g2[p] * osc; } }
;     ...
;                 for (int bj = 0; bj < 2; ++bj) { const f32x4 xs = *(const LAS f32x4*)(X + (rt * 2 + bj) * 4);
;                     const float tot = h128 ? ((xs[0] + xs[1]) + (xs[2] + xs[3])) : ((wc & 2) ? (xs[2] + xs[3]) : (xs[0] + xs[1]));
;                     const float rstd = rsqrtf(tot * inv_w + EPS);
;                     const f32x4 v0 = acc[ai][bj][m][0], v1 = acc[ai][bj][m][1];
;                     float o[8]; const float e[8] = {v0[0], v0[1], v0[2], v0[3], v1[0], v1[1], v1[2], v1[3]};
; #pragma unroll
;                     for (int p = 0; p < 4; ++p) { const float x1 = e[2 * p] * rstd * ga[p], x2 = e[2 * p + 1] * rstd * gb[p];
;                         o[2 * p] = x1 * cs[p] - x2 * sn[p]; o[2 * p + 1] = x2 * cs[p] + x1 * sn[p]; }
;                     *(u32x4*)(rowp + bj * HALF) = pack8(o); }
.LBB0_412:
	s_waitcnt lgkmcnt(0)
	v_fma_f32 v128, s45, v179, v168
	v_cmp_gt_f32_e32 vcc, s85, v128
	v_mul_f32_e32 v129, 0x4b800000, v128
	s_nop 0
	v_cndmask_b32_e32 v128, v128, v129, vcc
	v_rsq_f32_e32 v128, v128
	s_nop 0
	v_mul_f32_e32 v129, 0x45800000, v128
	v_cndmask_b32_e32 v128, v128, v129, vcc
	v_mul_f32_e32 v130, v21, v128
	v_mul_f32_e32 v129, v20, v128
	v_mul_f32_e32 v130, v174, v130
	v_mul_f32_e32 v129, v175, v129
	v_mul_f32_e32 v131, v177, v130
	v_fma_f32 v131, v135, v129, -v131
	v_mul_f32_e32 v130, v135, v130
	v_mul_f32_e32 v135, v23, v128
	v_fmac_f32_e32 v130, v177, v129
	v_mul_f32_e32 v129, v22, v128
	v_mul_f32_e32 v135, v173, v135
	v_mul_f32_e32 v129, v139, v129
	v_mul_f32_e32 v139, v181, v135
	v_mul_f32_e32 v135, v178, v135
	v_fma_f32 v139, v178, v129, -v139
	v_fmac_f32_e32 v135, v181, v129
	v_mul_f32_e32 v129, v16, v128
	v_mul_f32_e32 v129, v138, v129
	v_mul_f32_e32 v138, v17, v128
	v_mul_f32_e32 v137, v137, v138
	v_mul_f32_e32 v138, v182, v137
	v_mul_f32_e32 v137, v180, v137
	v_fma_f32 v138, v180, v129, -v138
	v_fmac_f32_e32 v137, v182, v129
	v_mul_f32_e32 v129, v18, v128
	v_mul_f32_e32 v128, v19, v128
	v_mul_f32_e32 v128, v134, v128
	v_mul_f32_e32 v129, v136, v129
	v_mul_f32_e32 v134, v184, v128
	v_mul_f32_e32 v136, v183, v128
	v_fma_f32 v134, v183, v129, -v134
	v_fmac_f32_e32 v136, v184, v129
	v_cvt_pk_bf16_f32 v128, v131, v130
	v_cvt_pk_bf16_f32 v129, v139, v135
	v_cvt_pk_bf16_f32 v130, v138, v137
	v_cvt_pk_bf16_f32 v131, v134, v136
	global_store_dwordx4 v[132:133], v[128:131], off offset:256
	v_add_u32_e32 v177, 0xb0, v171
	v_lshl_add_u64 v[132:133], v[158:159], 0, s[22:23]
	v_mov_b32_e32 v128, v194
	v_mov_b32_e32 v129, v195
	v_mov_b32_e32 v130, v196
	v_mov_b32_e32 v131, v197
	v_mov_b32_e32 v132, v198
	v_mov_b32_e32 v133, v199
	v_mov_b32_e32 v134, v200
	v_mov_b32_e32 v135, v201
	v_lshlrev_b32_e32 v173, 5, v177
	v_add_u32_e32 v136, 0, v173
	v_add_u32_e32 v136, 0x20000, v136
	ds_read_b128 v[136:139], v136
	s_and_b64 vcc, exec, s[2:3]
	s_mov_b64 s[0:1], -1
	s_cbranch_vccnz .LBB0_418
	s_and_b64 vcc, exec, s[4:5]
	s_cbranch_vccnz .LBB0_415
	s_waitcnt lgkmcnt(0)
	v_add_f32_e32 v178, v138, v139
	s_mov_b64 s[0:1], 0

; #define LAS __attribute__((address_space(3)))
;     __device__ __forceinline__ void operator()(const Acc& acc, const Unit& u, int wr, int wc, int fr_, int fq_) const {
;     ...
;             for (int m = 0; m < 4; ++m) { const int rt = ai * HALF + wr * 64 + m * 16 + fr;
;                 const int sp = (u.pm & 15) * BM + rt; const float pos = userow ? (float)(sp >> 6) : (float)(sp & 63);
;                 float cs[4], sn[4], ga[4], gb[4];
;                 { const float* gp = g + t0; asm volatile("" : "+v"(gp));
;                   const f32x4 g1 = *(const f32x4*)gp, g2 = *(const f32x4*)(gp + hd2);
; #pragma unroll
;                   for (int p = 0; p < 4; ++p) { ga[p] = g1[p] * osc; gb[p] = g2[p] * osc; } }
; #pragma unroll
;                 for (int p = 0; p < 4; ++p) { const float ang = pos * __builtin_amdgcn_exp2f(-(float)((t0 + p) & (nf - 1)) * (13.287712379549449f / (float)nf));
;                     cs[p] = rope ? __cosf(ang) : 1.f; sn[p] = rope ? __sinf(ang) : 0.f; }
;                 bf16_t* rowp = base + (size_t)(rowbase + rt) * ld + col0;
; #pragma unroll
;                 for (int bj = 0; bj < 2; ++bj) { const f32x4 xs = *(const LAS f32x4*)(X + (rt * 2 + bj) * 4);
;                     const float tot = h128 ? ((xs[0] + xs[1]) + (xs[2] + xs[3])) : ((wc & 2) ? (xs[2] + xs[3]) : (xs[0] + xs[1]));
;                     const float rstd = rsqrtf(tot * inv_w + EPS);
;                     const f32x4 v0 = acc[ai][bj][m][0], v1 = acc[ai][bj][m][1];
;                     float o[8]; const float e[8] = {v0[0], v0[1], v0[2], v0[3], v1[0], v1[1], v1[2], v1[3]};
; #pragma unroll
;                     for (int p = 0; p < 4; ++p) { const float x1 = e[2 * p] * rstd * ga[p], x2 = e[2 * p + 1] * rstd * gb[p];
;                         o[2 * p] = x1 * cs[p] - x2 * sn[p]; o[2 * p + 1] = x2 * cs[p] + x1 * sn[p]; }
;                     *(u32x4*)(rowp + bj * HALF) = pack8(o); }
.LBB0_420:
	s_waitcnt lgkmcnt(0)
	v_add_u32_e32 v136, s87, v177
	v_ashrrev_i32_e32 v136, 6, v136
	v_cvt_f32_i32_e32 v136, v136
	s_nop 0
	v_mul_f32_e32 v171, s43, v128
	v_mul_f32_e32 v139, s43, v129
	v_mul_f32_e32 v137, s43, v134
	v_cndmask_b32_e64 v176, v176, v136, s[8:9]
	v_mul_f32_e32 v128, v176, v155
	v_mul_f32_e32 v128, 0.15915494, v128
	v_cos_f32_e32 v129, v128
	v_sin_f32_e32 v128, v128
	v_mul_f32_e32 v134, s43, v135
	v_mul_f32_e32 v159, s43, v132
	v_cndmask_b32_e64 v135, 1.0, v129, s[6:7]
	v_cndmask_b32_e64 v155, 0, v128, s[6:7]
	v_mul_f32_e32 v128, v176, v161
	v_mul_f32_e32 v128, 0.15915494, v128
	v_cos_f32_e32 v129, v128
	v_sin_f32_e32 v128, v128
	v_mul_f32_e32 v158, s43, v133
	v_mul_f32_e32 v138, s43, v130
	v_cndmask_b32_e64 v161, 1.0, v129, s[6:7]
	v_cndmask_b32_e64 v174, 0, v128, s[6:7]
	v_mul_f32_e32 v128, v176, v172
	v_mul_f32_e32 v128, 0.15915494, v128
	v_cos_f32_e32 v129, v128
	v_sin_f32_e32 v128, v128
	v_mul_f32_e32 v136, s43, v131
	v_cndmask_b32_e64 v172, 1.0, v129, s[6:7]
	v_cndmask_b32_e64 v175, 0, v128, s[6:7]
	v_mul_f32_e32 v128, v176, v160
	v_mul_f32_e32 v128, 0.15915494, v128
	v_cos_f32_e32 v129, v128
	v_sin_f32_e32 v128, v128
	v_cndmask_b32_e64 v160, 1.0, v129, s[6:7]
	v_cndmask_b32_e64 v176, 0, v128, s[6:7]
	v_add_u32_e32 v128, s35, v177
	v_mad_i64_i32 v[128:129], s[0:1], s86, v128, 0
	v_lshl_add_u64 v[132:133], v[128:129], 1, v[156:157]
	v_fma_f32 v128, s45, v178, v168
	v_cmp_gt_f32_e32 vcc, s85, v128
	v_mul_f32_e32 v129, 0x4b800000, v128
	s_mov_b64 s[0:1], -1
	v_cndmask_b32_e32 v128, v128, v129, vcc
	v_rsq_f32_e32 v128, v128
	s_nop 0
	v_mul_f32_e32 v129, 0x45800000, v128
	v_cndmask_b32_e32 v128, v128, v129, vcc
	v_mul_f32_e32 v130, v13, v128
	v_mul_f32_e32 v129, v12, v128
	v_mul_f32_e32 v130, v159, v130
	v_mul_f32_e32 v129, v171, v129
	v_mul_f32_e32 v131, v155, v130
	v_mul_f32_e32 v130, v135, v130
	v_mul_f32_e32 v156, v15, v128
	v_fma_f32 v131, v135, v129, -v131
	v_fmac_f32_e32 v130, v155, v129
	v_mul_f32_e32 v129, v14, v128
	v_mul_f32_e32 v156, v158, v156
	v_mul_f32_e32 v129, v139, v129
	v_mul_f32_e32 v157, v174, v156
	v_mul_f32_e32 v156, v161, v156
	v_mul_f32_e32 v177, v9, v128
	v_fma_f32 v157, v161, v129, -v157
	v_fmac_f32_e32 v156, v174, v129
	v_mul_f32_e32 v129, v8, v128
	v_mul_f32_e32 v177, v137, v177
	v_mul_f32_e32 v129, v138, v129
	v_mul_f32_e32 v178, v175, v177
	v_mul_f32_e32 v177, v172, v177
	v_fma_f32 v178, v172, v129, -v178
	v_fmac_f32_e32 v177, v175, v129
	v_mul_f32_e32 v129, v10, v128
	v_mul_f32_e32 v128, v11, v128
	v_mul_f32_e32 v128, v134, v128
	v_mul_f32_e32 v129, v136, v129
	v_mul_f32_e32 v179, v176, v128
	v_mul_f32_e32 v180, v160, v128
	v_cvt_pk_bf16_f32 v128, v131, v130
	v_fma_f32 v179, v160, v129, -v179
	v_fmac_f32_e32 v180, v176, v129
	v_cvt_pk_bf16_f32 v129, v157, v156
	v_cvt_pk_bf16_f32 v130, v178, v177
	v_cvt_pk_bf16_f32 v131, v179, v180
	global_store_dwordx4 v[132:133], v[128:131], off
	s_and_b64 vcc, exec, s[2:3]
	s_nop 0
	v_add_u32_e32 v128, s95, v173
	ds_read_b128 v[128:131], v128 offset:16
	s_cbranch_vccnz .LBB0_426
	s_and_b64 vcc, exec, s[4:5]
	s_cbranch_vccnz .LBB0_423
	s_waitcnt lgkmcnt(0)
	v_add_f32_e32 v156, v130, v131
	s_mov_b64 s[0:1], 0
